# nt hint on GEMM1 epilogue stores; NA loop: counted vmcnt so half-0 output stores stay in flight
# speedup vs baseline: 1.0376x; 1.0376x over previous
.LBB0_278:
	v_fmamk_f32 v56, v56, 0x3a800000, v235
	v_rsq_f32_e32 v174, v56
	v_fmamk_f32 v56, v57, 0x3a800000, v235
	v_fmamk_f32 v50, v50, 0x3a800000, v235
	v_rsq_f32_e32 v175, v56
	v_rsq_f32_e32 v56, v50
	v_fmamk_f32 v50, v51, 0x3a800000, v235
	v_rsq_f32_e32 v57, v50
	v_fmamk_f32 v50, v52, 0x3a800000, v235
	v_rsq_f32_e32 v176, v50
	v_fmamk_f32 v50, v53, 0x3a800000, v235
	v_fmamk_f32 v54, v54, 0x3a800000, v235
	v_fmamk_f32 v55, v55, 0x3a800000, v235
	v_rsq_f32_e32 v177, v50
	v_rsq_f32_e32 v54, v54
	v_rsq_f32_e32 v55, v55
	v_add_u32_e32 v173, s0, v204
	v_mov_b64_e32 v[50:51], s[84:85]
	v_mad_i64_i32 v[50:51], s[22:23], v173, s8, v[50:51]
	v_lshl_add_u64 v[184:185], v[70:71], 1, v[50:51]
	v_mov_b32_e32 v50, v170
	v_mov_b32_e32 v51, v170
	v_mov_b32_e32 v171, v170
	global_store_dwordx4 v[184:185], v[66:69], off nt
	v_pk_fma_f32 v[198:199], v[132:133], v[176:177], v[50:51]
	v_pk_fma_f32 v[200:201], v[130:131], v[56:57], v[170:171]
	v_pk_fma_f32 v[66:67], v[136:137], v[174:175], v[50:51]
	v_cndmask_b32_e64 v50, 0, 1, s[16:17]
	v_pk_fma_f32 v[68:69], v[134:135], v[54:55], v[170:171]
	v_cmp_ne_u32_e64 s[40:41], 1, v50
	s_andn2_b64 vcc, exec, s[16:17]
	s_mov_b64 s[16:17], -1
	s_cbranch_vccnz .LBB0_280
	v_cvt_pk_f16_f32 v50, v68, v69
	v_cvt_pk_f16_f32 v51, v66, v67
	v_cvt_pk_f16_f32 v52, v200, v201
	v_cvt_pk_f16_f32 v53, v198, v199
	s_mov_b64 s[16:17], 0

.LBB0_282:
	global_store_dwordx4 v[184:185], v[50:53], off offset:256 nt
	v_pk_fma_f32 v[66:67], v[128:129], v[152:153], v[168:169] op_sel_hi:[1,1,0]
	v_pk_fma_f32 v[68:69], v[126:127], v[150:151], v[168:169] op_sel_hi:[1,1,0]
	v_pk_fma_f32 v[184:185], v[124:125], v[148:149], v[168:169] op_sel_hi:[1,1,0]
	v_pk_fma_f32 v[198:199], v[122:123], v[146:147], v[168:169] op_sel_hi:[1,1,0]
	s_and_b64 vcc, exec, s[40:41]
	s_mov_b64 s[16:17], -1
	s_cbranch_vccnz .LBB0_284
	v_cvt_pk_f16_f32 v50, v68, v69
	v_cvt_pk_f16_f32 v51, v66, v67
	v_cvt_pk_f16_f32 v52, v198, v199
	v_cvt_pk_f16_f32 v53, v184, v185
	s_mov_b64 s[16:17], 0

.LBB0_286:
	v_or_b32_e32 v68, 16, v173
	v_mov_b64_e32 v[66:67], s[84:85]
	v_mad_i64_i32 v[66:67], s[16:17], v68, s8, v[66:67]
	v_lshl_add_u64 v[66:67], v[70:71], 1, v[66:67]
	v_mov_b32_e32 v169, v168
	global_store_dwordx4 v[66:67], v[50:53], off nt
	v_pk_fma_f32 v[184:185], v[118:119], v[54:55], v[168:169]
	v_pk_fma_f32 v[200:201], v[114:115], v[56:57], v[168:169]
	v_mov_b32_e32 v50, v168
	v_mov_b32_e32 v51, v168
	v_pk_fma_f32 v[68:69], v[120:121], v[174:175], v[50:51]
	v_pk_fma_f32 v[198:199], v[116:117], v[176:177], v[50:51]
	s_and_b64 vcc, exec, s[40:41]
	s_mov_b64 s[16:17], -1
	s_cbranch_vccnz .LBB0_288
	v_cvt_pk_f16_f32 v50, v184, v185
	v_cvt_pk_f16_f32 v51, v68, v69
	v_cvt_pk_f16_f32 v52, v200, v201
	v_cvt_pk_f16_f32 v53, v198, v199
	s_mov_b64 s[16:17], 0

.LBB0_290:
	global_store_dwordx4 v[66:67], v[50:53], off offset:256 nt
	v_pk_fma_f32 v[66:67], v[112:113], v[152:153], v[166:167] op_sel_hi:[1,1,0]
	v_pk_fma_f32 v[68:69], v[110:111], v[150:151], v[166:167] op_sel_hi:[1,1,0]
	v_pk_fma_f32 v[184:185], v[108:109], v[148:149], v[166:167] op_sel_hi:[1,1,0]
	v_pk_fma_f32 v[198:199], v[106:107], v[146:147], v[166:167] op_sel_hi:[1,1,0]
	s_and_b64 vcc, exec, s[40:41]
	s_mov_b64 s[16:17], -1
	s_cbranch_vccnz .LBB0_292
	v_cvt_pk_f16_f32 v50, v68, v69
	v_cvt_pk_f16_f32 v51, v66, v67
	v_cvt_pk_f16_f32 v52, v198, v199
	v_cvt_pk_f16_f32 v53, v184, v185
	s_mov_b64 s[16:17], 0

.LBB0_294:
	v_or_b32_e32 v68, 32, v173
	v_mov_b64_e32 v[66:67], s[84:85]
	v_mad_i64_i32 v[66:67], s[16:17], v68, s8, v[66:67]
	v_lshl_add_u64 v[66:67], v[70:71], 1, v[66:67]
	v_mov_b32_e32 v167, v166
	global_store_dwordx4 v[66:67], v[50:53], off nt
	v_pk_fma_f32 v[184:185], v[102:103], v[54:55], v[166:167]
	v_pk_fma_f32 v[200:201], v[98:99], v[56:57], v[166:167]
	v_mov_b32_e32 v50, v166
	v_mov_b32_e32 v51, v166
	v_pk_fma_f32 v[68:69], v[104:105], v[174:175], v[50:51]
	v_pk_fma_f32 v[198:199], v[100:101], v[176:177], v[50:51]
	s_and_b64 vcc, exec, s[40:41]
	s_mov_b64 s[16:17], -1
	s_cbranch_vccnz .LBB0_296
	v_cvt_pk_f16_f32 v50, v184, v185
	v_cvt_pk_f16_f32 v51, v68, v69
	v_cvt_pk_f16_f32 v52, v200, v201
	v_cvt_pk_f16_f32 v53, v198, v199
	s_mov_b64 s[16:17], 0

.LBB0_298:
	global_store_dwordx4 v[66:67], v[50:53], off offset:256 nt
	v_pk_fma_f32 v[66:67], v[96:97], v[152:153], v[164:165] op_sel_hi:[1,1,0]
	v_pk_fma_f32 v[68:69], v[94:95], v[150:151], v[164:165] op_sel_hi:[1,1,0]
	v_pk_fma_f32 v[184:185], v[92:93], v[148:149], v[164:165] op_sel_hi:[1,1,0]
	v_pk_fma_f32 v[198:199], v[90:91], v[146:147], v[164:165] op_sel_hi:[1,1,0]
	s_and_b64 vcc, exec, s[40:41]
	s_mov_b64 s[16:17], -1
	s_cbranch_vccnz .LBB0_300
	v_cvt_pk_f16_f32 v50, v68, v69
	v_cvt_pk_f16_f32 v51, v66, v67
	v_cvt_pk_f16_f32 v52, v198, v199
	v_cvt_pk_f16_f32 v53, v184, v185
	s_mov_b64 s[16:17], 0

.LBB0_302:
	v_or_b32_e32 v68, 48, v173
	v_mov_b64_e32 v[66:67], s[84:85]
	v_mad_i64_i32 v[66:67], s[16:17], v68, s8, v[66:67]
	v_lshl_add_u64 v[66:67], v[70:71], 1, v[66:67]
	v_mov_b32_e32 v165, v164
	global_store_dwordx4 v[66:67], v[50:53], off nt
	v_pk_fma_f32 v[184:185], v[86:87], v[54:55], v[164:165]
	v_pk_fma_f32 v[200:201], v[82:83], v[56:57], v[164:165]
	v_mov_b32_e32 v50, v164
	v_mov_b32_e32 v51, v164
	v_pk_fma_f32 v[68:69], v[88:89], v[174:175], v[50:51]
	v_pk_fma_f32 v[198:199], v[84:85], v[176:177], v[50:51]
	s_and_b64 vcc, exec, s[40:41]
	s_mov_b64 s[16:17], -1
	s_cbranch_vccnz .LBB0_304
	v_cvt_pk_f16_f32 v50, v184, v185
	v_cvt_pk_f16_f32 v51, v68, v69
	v_cvt_pk_f16_f32 v52, v200, v201
	v_cvt_pk_f16_f32 v53, v198, v199
	s_mov_b64 s[16:17], 0

.LBB0_306:
	global_store_dwordx4 v[66:67], v[50:53], off offset:256 nt
	v_pk_fma_f32 v[66:67], v[80:81], v[152:153], v[182:183] op_sel_hi:[1,1,0]
	v_pk_fma_f32 v[68:69], v[78:79], v[150:151], v[182:183] op_sel_hi:[1,1,0]
	v_pk_fma_f32 v[184:185], v[76:77], v[148:149], v[182:183] op_sel_hi:[1,1,0]
	v_pk_fma_f32 v[198:199], v[74:75], v[146:147], v[182:183] op_sel_hi:[1,1,0]
	s_and_b64 vcc, exec, s[40:41]
	s_mov_b64 s[16:17], -1
	s_cbranch_vccnz .LBB0_308
	v_cvt_pk_f16_f32 v50, v68, v69
	v_cvt_pk_f16_f32 v51, v66, v67
	v_cvt_pk_f16_f32 v52, v198, v199
	v_cvt_pk_f16_f32 v53, v184, v185
	s_mov_b64 s[16:17], 0

.LBB0_310:
	v_add_u32_e32 v68, 0x80, v173
	v_mov_b64_e32 v[66:67], s[84:85]
	v_mad_i64_i32 v[66:67], s[16:17], v68, s8, v[66:67]
	v_lshl_add_u64 v[66:67], v[70:71], 1, v[66:67]
	v_mov_b32_e32 v183, v182
	global_store_dwordx4 v[66:67], v[50:53], off nt
	v_pk_fma_f32 v[184:185], v[62:63], v[54:55], v[182:183]
	s_and_b64 vcc, exec, s[40:41]
	v_mov_b32_e32 v50, v182
	v_mov_b32_e32 v51, v182
	v_pk_fma_f32 v[68:69], v[64:65], v[174:175], v[50:51]
	v_pk_fma_f32 v[198:199], v[60:61], v[176:177], v[50:51]
	v_pk_fma_f32 v[182:183], v[58:59], v[56:57], v[182:183]
	s_mov_b64 s[16:17], -1
	s_cbranch_vccnz .LBB0_312
	v_cvt_pk_f16_f32 v50, v184, v185
	v_cvt_pk_f16_f32 v51, v68, v69
	v_cvt_pk_f16_f32 v52, v182, v183
	v_cvt_pk_f16_f32 v53, v198, v199
	s_mov_b64 s[16:17], 0

.LBB0_314:
	global_store_dwordx4 v[66:67], v[50:53], off offset:256 nt
	v_pk_fma_f32 v[66:67], v[48:49], v[152:153], v[180:181] op_sel_hi:[1,1,0]
	v_pk_fma_f32 v[68:69], v[46:47], v[150:151], v[180:181] op_sel_hi:[1,1,0]
	v_pk_fma_f32 v[182:183], v[44:45], v[148:149], v[180:181] op_sel_hi:[1,1,0]
	v_pk_fma_f32 v[184:185], v[42:43], v[146:147], v[180:181] op_sel_hi:[1,1,0]
	s_and_b64 vcc, exec, s[40:41]
	s_mov_b64 s[16:17], -1
	s_cbranch_vccnz .LBB0_316
	v_cvt_pk_f16_f32 v50, v68, v69
	v_cvt_pk_f16_f32 v51, v66, v67
	v_cvt_pk_f16_f32 v52, v184, v185
	v_cvt_pk_f16_f32 v53, v182, v183
	s_mov_b64 s[16:17], 0

.LBB0_318:
	v_add_u32_e32 v68, 0x90, v173
	v_mov_b64_e32 v[66:67], s[84:85]
	v_mad_i64_i32 v[66:67], s[16:17], v68, s8, v[66:67]
	v_lshl_add_u64 v[66:67], v[70:71], 1, v[66:67]
	v_mov_b32_e32 v181, v180
	global_store_dwordx4 v[66:67], v[50:53], off nt
	v_pk_fma_f32 v[182:183], v[38:39], v[54:55], v[180:181]
	s_and_b64 vcc, exec, s[40:41]
	v_mov_b32_e32 v50, v180
	v_mov_b32_e32 v51, v180
	v_pk_fma_f32 v[68:69], v[40:41], v[174:175], v[50:51]
	v_pk_fma_f32 v[184:185], v[36:37], v[176:177], v[50:51]
	v_pk_fma_f32 v[180:181], v[34:35], v[56:57], v[180:181]
	s_mov_b64 s[16:17], -1
	s_cbranch_vccnz .LBB0_320
	v_cvt_pk_f16_f32 v50, v182, v183
	v_cvt_pk_f16_f32 v51, v68, v69
	v_cvt_pk_f16_f32 v52, v180, v181
	v_cvt_pk_f16_f32 v53, v184, v185
	s_mov_b64 s[16:17], 0

.LBB0_322:
	global_store_dwordx4 v[66:67], v[50:53], off offset:256 nt
	v_pk_fma_f32 v[66:67], v[32:33], v[152:153], v[178:179] op_sel_hi:[1,1,0]
	v_pk_fma_f32 v[68:69], v[30:31], v[150:151], v[178:179] op_sel_hi:[1,1,0]
	v_pk_fma_f32 v[180:181], v[28:29], v[148:149], v[178:179] op_sel_hi:[1,1,0]
	v_pk_fma_f32 v[182:183], v[26:27], v[146:147], v[178:179] op_sel_hi:[1,1,0]
	s_and_b64 vcc, exec, s[40:41]
	s_mov_b64 s[16:17], -1
	s_cbranch_vccnz .LBB0_324
	v_cvt_pk_f16_f32 v50, v68, v69
	v_cvt_pk_f16_f32 v51, v66, v67
	v_cvt_pk_f16_f32 v52, v182, v183
	v_cvt_pk_f16_f32 v53, v180, v181
	s_mov_b64 s[16:17], 0

.LBB0_326:
	v_add_u32_e32 v68, 0xa0, v173
	v_mov_b64_e32 v[66:67], s[84:85]
	v_mad_i64_i32 v[66:67], s[16:17], v68, s8, v[66:67]
	v_lshl_add_u64 v[66:67], v[70:71], 1, v[66:67]
	v_mov_b32_e32 v179, v178
	global_store_dwordx4 v[66:67], v[50:53], off nt
	v_pk_fma_f32 v[180:181], v[22:23], v[54:55], v[178:179]
	s_and_b64 vcc, exec, s[40:41]
	v_mov_b32_e32 v50, v178
	v_mov_b32_e32 v51, v178
	v_pk_fma_f32 v[68:69], v[24:25], v[174:175], v[50:51]
	v_pk_fma_f32 v[182:183], v[20:21], v[176:177], v[50:51]
	v_pk_fma_f32 v[178:179], v[18:19], v[56:57], v[178:179]
	s_mov_b64 s[16:17], -1
	s_cbranch_vccnz .LBB0_328
	v_cvt_pk_f16_f32 v50, v180, v181
	v_cvt_pk_f16_f32 v51, v68, v69
	v_cvt_pk_f16_f32 v52, v178, v179
	v_cvt_pk_f16_f32 v53, v182, v183
	s_mov_b64 s[16:17], 0

.LBB0_330:
	global_store_dwordx4 v[66:67], v[50:53], off offset:256 nt
	v_pk_fma_f32 v[66:67], v[16:17], v[152:153], v[72:73] op_sel_hi:[1,1,0]
	v_pk_fma_f32 v[68:69], v[14:15], v[150:151], v[72:73] op_sel_hi:[1,1,0]
	v_pk_fma_f32 v[148:149], v[12:13], v[148:149], v[72:73] op_sel_hi:[1,1,0]
	v_pk_fma_f32 v[146:147], v[10:11], v[146:147], v[72:73] op_sel_hi:[1,1,0]
	s_and_b64 vcc, exec, s[40:41]
	s_mov_b64 s[16:17], -1
	s_cbranch_vccnz .LBB0_332
	v_cvt_pk_f16_f32 v50, v68, v69
	v_cvt_pk_f16_f32 v51, v66, v67
	v_cvt_pk_f16_f32 v52, v146, v147
	v_cvt_pk_f16_f32 v53, v148, v149
	s_mov_b64 s[16:17], 0

.LBB0_334:
	v_add_u32_e32 v68, 0xb0, v173
	v_mov_b64_e32 v[66:67], s[84:85]
	v_mad_i64_i32 v[66:67], s[16:17], v68, s8, v[66:67]
	v_lshl_add_u64 v[66:67], v[70:71], 1, v[66:67]
	v_mov_b32_e32 v73, v72
	global_store_dwordx4 v[66:67], v[50:53], off nt
	v_pk_fma_f32 v[54:55], v[6:7], v[54:55], v[72:73]
	v_pk_fma_f32 v[56:57], v[2:3], v[56:57], v[72:73]
	v_mov_b32_e32 v50, v72
	v_mov_b32_e32 v51, v72
	v_pk_fma_f32 v[68:69], v[8:9], v[174:175], v[50:51]
	v_pk_fma_f32 v[70:71], v[4:5], v[176:177], v[50:51]
	s_and_b64 vcc, exec, s[40:41]
	s_mov_b64 s[16:17], -1
	s_cbranch_vccnz .LBB0_336
	v_cvt_pk_f16_f32 v50, v54, v55
	v_cvt_pk_f16_f32 v51, v68, v69
	v_cvt_pk_f16_f32 v52, v56, v57
	v_cvt_pk_f16_f32 v53, v70, v71
	s_mov_b64 s[16:17], 0

.LBB0_338:
.LBB0_339:
	s_and_b64 vcc, exec, s[38:39]
	s_mov_b64 s[14:15], -1
	global_store_dwordx4 v[66:67], v[50:53], off offset:256 nt
	s_cbranch_vccnz .LBB0_262
	s_branch .LBB0_470

.LBB0_349:
	v_mov_b64_e32 v[138:139], s[68:69]
	v_mad_i64_i32 v[138:139], s[0:1], v172, s9, v[138:139]
	v_lshl_add_u64 v[180:181], v[174:175], 1, v[138:139]
	v_cvt_pk_bf16_f32 v138, v146, v147
	v_cvt_pk_bf16_f32 v139, v148, v149
	v_cvt_pk_bf16_f32 v140, v150, v151
	v_cvt_pk_bf16_f32 v141, v152, v153
	global_store_dwordx4 v[180:181], v[138:141], off nt
	v_mov_b32_e32 v179, v178
	v_pk_fma_f32 v[134:135], v[178:179], v[134:135], v[54:55]
	v_mov_b32_e32 v138, v178
	v_mov_b32_e32 v139, v178
	v_pk_fma_f32 v[136:137], v[138:139], v[136:137], v[56:57]
	v_pk_fma_f32 v[132:133], v[138:139], v[132:133], v[52:53]
	v_pk_fma_f32 v[130:131], v[178:179], v[130:131], v[50:51]
	s_cmp_lt_i32 s16, 2
	s_mov_b64 s[14:15], -1
	s_cbranch_scc1 .LBB0_353
	v_mov_b64_e32 v[144:145], v[132:133]
	v_mov_b64_e32 v[140:141], v[136:137]
	s_cmp_eq_u32 s16, 2
	v_mov_b64_e32 v[142:143], v[130:131]
	v_mov_b64_e32 v[138:139], v[134:135]
	s_cbranch_scc0 .LBB0_352
	v_mul_f32_e32 v139, 0x3d372713, v130
	v_mul_f32_e32 v139, v130, v139
	v_mul_f32_e32 v140, 0x3d372713, v135
	v_fma_f32 v139, v130, v139, v130
	v_mul_f32_e32 v140, v135, v140
	v_mul_f32_e32 v139, 0x3fcc422a, v139
	v_fma_f32 v140, v135, v140, v135
	v_mul_f32_e32 v139, 0xbfb8aa3b, v139
	v_mul_f32_e32 v140, 0x3fcc422a, v140
	v_exp_f32_e32 v139, v139
	v_mul_f32_e32 v140, 0xbfb8aa3b, v140
	v_exp_f32_e32 v140, v140
	v_mul_f32_e32 v141, 0x3d372713, v136
	v_add_f32_e32 v139, 1.0, v139
	v_rcp_f32_e32 v142, v139
	v_add_f32_e32 v139, 1.0, v140
	v_mul_f32_e32 v140, 0x3d372713, v131
	v_mul_f32_e32 v143, 0x3d372713, v132
	v_mul_f32_e32 v140, v131, v140
	v_mul_f32_e32 v141, v136, v141
	v_mul_f32_e32 v143, v132, v143
	v_fma_f32 v140, v131, v140, v131
	v_fma_f32 v141, v136, v141, v136
	v_fma_f32 v143, v132, v143, v132
	v_mul_f32_e32 v140, 0x3fcc422a, v140
	v_mul_f32_e32 v141, 0x3fcc422a, v141
	v_mul_f32_e32 v143, 0x3fcc422a, v143
	v_mul_f32_e32 v140, 0xbfb8aa3b, v140
	v_mul_f32_e32 v141, 0xbfb8aa3b, v141
	v_mul_f32_e32 v143, 0xbfb8aa3b, v143
	v_exp_f32_e32 v140, v140
	v_exp_f32_e32 v141, v141
	v_exp_f32_e32 v143, v143
	v_mul_f32_e32 v138, 0x3d372713, v134
	v_add_f32_e32 v146, 1.0, v140
	v_add_f32_e32 v140, 1.0, v141
	v_add_f32_e32 v141, 1.0, v143
	v_mul_f32_e32 v143, 0x3d372713, v137
	v_mul_f32_e32 v144, 0x3d372713, v133
	v_mul_f32_e32 v138, v134, v138
	v_mul_f32_e32 v143, v137, v143
	v_mul_f32_e32 v144, v133, v144
	v_fma_f32 v138, v134, v138, v134
	v_fma_f32 v143, v137, v143, v137
	v_fma_f32 v144, v133, v144, v133
	v_mul_f32_e32 v138, 0x3fcc422a, v138
	v_mul_f32_e32 v143, 0x3fcc422a, v143
	v_mul_f32_e32 v144, 0x3fcc422a, v144
	v_mul_f32_e32 v138, 0xbfb8aa3b, v138
	v_mul_f32_e32 v143, 0xbfb8aa3b, v143
	v_mul_f32_e32 v144, 0xbfb8aa3b, v144
	v_exp_f32_e32 v138, v138
	v_exp_f32_e32 v143, v143
	v_exp_f32_e32 v145, v144
	v_rcp_f32_e32 v144, v141
	v_add_f32_e32 v138, 1.0, v138
	v_add_f32_e32 v141, 1.0, v143
	v_add_f32_e32 v143, 1.0, v145
	v_rcp_f32_e32 v138, v138
	v_rcp_f32_e32 v139, v139
	v_rcp_f32_e32 v140, v140
	v_rcp_f32_e32 v141, v141
	v_rcp_f32_e32 v145, v143
	v_rcp_f32_e32 v143, v146
	v_pk_mul_f32 v[138:139], v[134:135], v[138:139]
	v_pk_mul_f32 v[140:141], v[136:137], v[140:141]
	v_pk_mul_f32 v[144:145], v[132:133], v[144:145]
	v_pk_mul_f32 v[142:143], v[130:131], v[142:143]

.LBB0_357:
	v_cvt_pk_bf16_f32 v130, v138, v139
	v_cvt_pk_bf16_f32 v131, v140, v141
	v_cvt_pk_bf16_f32 v132, v142, v143
	v_cvt_pk_bf16_f32 v133, v144, v145
	global_store_dwordx4 v[180:181], v[130:133], off offset:256 nt
	s_cmp_lt_i32 s16, 2
	s_mov_b64 s[14:15], -1
	v_fmamk_f32 v130, v168, 0x3a800000, v235
	v_rsq_f32_e32 v138, v130
	s_nop 0
	v_pk_fma_f32 v[128:129], v[138:139], v[128:129], v[72:73] op_sel_hi:[0,1,1]
	v_pk_fma_f32 v[126:127], v[138:139], v[126:127], v[70:71] op_sel_hi:[0,1,1]
	v_pk_fma_f32 v[124:125], v[138:139], v[124:125], v[68:69] op_sel_hi:[0,1,1]
	v_pk_fma_f32 v[122:123], v[138:139], v[122:123], v[66:67] op_sel_hi:[0,1,1]
	s_cbranch_scc1 .LBB0_361
	v_mov_b64_e32 v[136:137], v[124:125]
	v_mov_b64_e32 v[132:133], v[128:129]
	s_cmp_eq_u32 s16, 2
	v_mov_b64_e32 v[134:135], v[122:123]
	v_mov_b64_e32 v[130:131], v[126:127]
	s_cbranch_scc0 .LBB0_360
	v_mul_f32_e32 v131, 0x3d372713, v122
	v_mul_f32_e32 v131, v122, v131
	v_mul_f32_e32 v132, 0x3d372713, v127
	v_fma_f32 v131, v122, v131, v122
	v_mul_f32_e32 v132, v127, v132
	v_mul_f32_e32 v131, 0x3fcc422a, v131
	v_fma_f32 v132, v127, v132, v127
	v_mul_f32_e32 v131, 0xbfb8aa3b, v131
	v_mul_f32_e32 v132, 0x3fcc422a, v132
	v_exp_f32_e32 v131, v131
	v_mul_f32_e32 v132, 0xbfb8aa3b, v132
	v_exp_f32_e32 v132, v132
	v_mul_f32_e32 v133, 0x3d372713, v128
	v_add_f32_e32 v131, 1.0, v131
	v_rcp_f32_e32 v134, v131
	v_add_f32_e32 v131, 1.0, v132
	v_mul_f32_e32 v132, 0x3d372713, v123
	v_mul_f32_e32 v135, 0x3d372713, v124
	v_mul_f32_e32 v132, v123, v132
	v_mul_f32_e32 v133, v128, v133
	v_mul_f32_e32 v135, v124, v135
	v_fma_f32 v132, v123, v132, v123
	v_fma_f32 v133, v128, v133, v128
	v_fma_f32 v135, v124, v135, v124
	v_mul_f32_e32 v132, 0x3fcc422a, v132
	v_mul_f32_e32 v133, 0x3fcc422a, v133
	v_mul_f32_e32 v135, 0x3fcc422a, v135
	v_mul_f32_e32 v132, 0xbfb8aa3b, v132
	v_mul_f32_e32 v133, 0xbfb8aa3b, v133
	v_mul_f32_e32 v135, 0xbfb8aa3b, v135
	v_exp_f32_e32 v132, v132
	v_exp_f32_e32 v133, v133
	v_exp_f32_e32 v135, v135
	v_mul_f32_e32 v130, 0x3d372713, v126
	v_add_f32_e32 v139, 1.0, v132
	v_add_f32_e32 v132, 1.0, v133
	v_add_f32_e32 v133, 1.0, v135
	v_mul_f32_e32 v135, 0x3d372713, v129
	v_mul_f32_e32 v136, 0x3d372713, v125
	v_mul_f32_e32 v130, v126, v130
	v_mul_f32_e32 v135, v129, v135
	v_mul_f32_e32 v136, v125, v136
	v_fma_f32 v130, v126, v130, v126
	v_fma_f32 v135, v129, v135, v129
	v_fma_f32 v136, v125, v136, v125
	v_mul_f32_e32 v130, 0x3fcc422a, v130
	v_mul_f32_e32 v135, 0x3fcc422a, v135
	v_mul_f32_e32 v136, 0x3fcc422a, v136
	v_mul_f32_e32 v130, 0xbfb8aa3b, v130
	v_mul_f32_e32 v135, 0xbfb8aa3b, v135
	v_mul_f32_e32 v136, 0xbfb8aa3b, v136
	v_exp_f32_e32 v130, v130
	v_exp_f32_e32 v135, v135
	v_exp_f32_e32 v137, v136
	v_rcp_f32_e32 v136, v133
	v_add_f32_e32 v130, 1.0, v130
	v_add_f32_e32 v133, 1.0, v135
	v_add_f32_e32 v135, 1.0, v137
	v_rcp_f32_e32 v130, v130
	v_rcp_f32_e32 v131, v131
	v_rcp_f32_e32 v132, v132
	v_rcp_f32_e32 v133, v133
	v_rcp_f32_e32 v137, v135
	v_rcp_f32_e32 v135, v139
	v_pk_mul_f32 v[130:131], v[126:127], v[130:131]
	v_pk_mul_f32 v[132:133], v[128:129], v[132:133]
	v_pk_mul_f32 v[136:137], v[124:125], v[136:137]
	v_pk_mul_f32 v[134:135], v[122:123], v[134:135]

.LBB0_365:
	v_or_b32_e32 v124, 16, v172
	v_mov_b64_e32 v[122:123], s[68:69]
	v_mad_i64_i32 v[122:123], s[0:1], v124, s9, v[122:123]
	v_lshl_add_u64 v[140:141], v[174:175], 1, v[122:123]
	v_cvt_pk_bf16_f32 v122, v130, v131
	v_cvt_pk_bf16_f32 v123, v132, v133
	v_cvt_pk_bf16_f32 v124, v134, v135
	v_cvt_pk_bf16_f32 v125, v136, v137
	global_store_dwordx4 v[140:141], v[122:125], off nt
	v_mov_b32_e32 v139, v138
	v_pk_fma_f32 v[118:119], v[138:139], v[118:119], v[54:55]
	v_mov_b32_e32 v122, v138
	v_mov_b32_e32 v123, v138
	v_pk_fma_f32 v[120:121], v[122:123], v[120:121], v[56:57]
	v_pk_fma_f32 v[116:117], v[122:123], v[116:117], v[52:53]
	v_pk_fma_f32 v[114:115], v[138:139], v[114:115], v[50:51]
	s_cmp_lt_i32 s16, 2
	s_mov_b64 s[14:15], -1
	s_cbranch_scc1 .LBB0_369
	v_mov_b64_e32 v[128:129], v[116:117]
	v_mov_b64_e32 v[124:125], v[120:121]
	s_cmp_eq_u32 s16, 2
	v_mov_b64_e32 v[126:127], v[114:115]
	v_mov_b64_e32 v[122:123], v[118:119]
	s_cbranch_scc0 .LBB0_368
	v_mul_f32_e32 v123, 0x3d372713, v114
	v_mul_f32_e32 v123, v114, v123
	v_mul_f32_e32 v124, 0x3d372713, v119
	v_fma_f32 v123, v114, v123, v114
	v_mul_f32_e32 v124, v119, v124
	v_mul_f32_e32 v123, 0x3fcc422a, v123
	v_fma_f32 v124, v119, v124, v119
	v_mul_f32_e32 v123, 0xbfb8aa3b, v123
	v_mul_f32_e32 v124, 0x3fcc422a, v124
	v_exp_f32_e32 v123, v123
	v_mul_f32_e32 v124, 0xbfb8aa3b, v124
	v_exp_f32_e32 v124, v124
	v_mul_f32_e32 v125, 0x3d372713, v120
	v_add_f32_e32 v123, 1.0, v123
	v_rcp_f32_e32 v126, v123
	v_add_f32_e32 v123, 1.0, v124
	v_mul_f32_e32 v124, 0x3d372713, v115
	v_mul_f32_e32 v127, 0x3d372713, v116
	v_mul_f32_e32 v124, v115, v124
	v_mul_f32_e32 v125, v120, v125
	v_mul_f32_e32 v127, v116, v127
	v_fma_f32 v124, v115, v124, v115
	v_fma_f32 v125, v120, v125, v120
	v_fma_f32 v127, v116, v127, v116
	v_mul_f32_e32 v124, 0x3fcc422a, v124
	v_mul_f32_e32 v125, 0x3fcc422a, v125
	v_mul_f32_e32 v127, 0x3fcc422a, v127
	v_mul_f32_e32 v124, 0xbfb8aa3b, v124
	v_mul_f32_e32 v125, 0xbfb8aa3b, v125
	v_mul_f32_e32 v127, 0xbfb8aa3b, v127
	v_exp_f32_e32 v124, v124
	v_exp_f32_e32 v125, v125
	v_exp_f32_e32 v127, v127
	v_mul_f32_e32 v122, 0x3d372713, v118
	v_add_f32_e32 v130, 1.0, v124
	v_add_f32_e32 v124, 1.0, v125
	v_add_f32_e32 v125, 1.0, v127
	v_mul_f32_e32 v127, 0x3d372713, v121
	v_mul_f32_e32 v128, 0x3d372713, v117
	v_mul_f32_e32 v122, v118, v122
	v_mul_f32_e32 v127, v121, v127
	v_mul_f32_e32 v128, v117, v128
	v_fma_f32 v122, v118, v122, v118
	v_fma_f32 v127, v121, v127, v121
	v_fma_f32 v128, v117, v128, v117
	v_mul_f32_e32 v122, 0x3fcc422a, v122
	v_mul_f32_e32 v127, 0x3fcc422a, v127
	v_mul_f32_e32 v128, 0x3fcc422a, v128
	v_mul_f32_e32 v122, 0xbfb8aa3b, v122
	v_mul_f32_e32 v127, 0xbfb8aa3b, v127
	v_mul_f32_e32 v128, 0xbfb8aa3b, v128
	v_exp_f32_e32 v122, v122
	v_exp_f32_e32 v127, v127
	v_exp_f32_e32 v129, v128
	v_rcp_f32_e32 v128, v125
	v_add_f32_e32 v122, 1.0, v122
	v_add_f32_e32 v125, 1.0, v127
	v_add_f32_e32 v127, 1.0, v129
	v_rcp_f32_e32 v122, v122
	v_rcp_f32_e32 v123, v123
	v_rcp_f32_e32 v124, v124
	v_rcp_f32_e32 v125, v125
	v_rcp_f32_e32 v129, v127
	v_rcp_f32_e32 v127, v130
	v_pk_mul_f32 v[122:123], v[118:119], v[122:123]
	v_pk_mul_f32 v[124:125], v[120:121], v[124:125]
	v_pk_mul_f32 v[128:129], v[116:117], v[128:129]
	v_pk_mul_f32 v[126:127], v[114:115], v[126:127]

.LBB0_373:
	v_cvt_pk_bf16_f32 v114, v122, v123
	v_cvt_pk_bf16_f32 v115, v124, v125
	v_cvt_pk_bf16_f32 v116, v126, v127
	v_cvt_pk_bf16_f32 v117, v128, v129
	global_store_dwordx4 v[140:141], v[114:117], off offset:256 nt
	s_cmp_lt_i32 s16, 2
	s_mov_b64 s[14:15], -1
	v_fmamk_f32 v114, v166, 0x3a800000, v235
	v_rsq_f32_e32 v122, v114
	s_nop 0
	v_pk_fma_f32 v[112:113], v[122:123], v[112:113], v[72:73] op_sel_hi:[0,1,1]
	v_pk_fma_f32 v[110:111], v[122:123], v[110:111], v[70:71] op_sel_hi:[0,1,1]
	v_pk_fma_f32 v[108:109], v[122:123], v[108:109], v[68:69] op_sel_hi:[0,1,1]
	v_pk_fma_f32 v[106:107], v[122:123], v[106:107], v[66:67] op_sel_hi:[0,1,1]
	s_cbranch_scc1 .LBB0_377
	v_mov_b64_e32 v[120:121], v[108:109]
	v_mov_b64_e32 v[116:117], v[112:113]
	s_cmp_eq_u32 s16, 2
	v_mov_b64_e32 v[118:119], v[106:107]
	v_mov_b64_e32 v[114:115], v[110:111]
	s_cbranch_scc0 .LBB0_376
	v_mul_f32_e32 v115, 0x3d372713, v106
	v_mul_f32_e32 v115, v106, v115
	v_mul_f32_e32 v116, 0x3d372713, v111
	v_fma_f32 v115, v106, v115, v106
	v_mul_f32_e32 v116, v111, v116
	v_mul_f32_e32 v115, 0x3fcc422a, v115
	v_fma_f32 v116, v111, v116, v111
	v_mul_f32_e32 v115, 0xbfb8aa3b, v115
	v_mul_f32_e32 v116, 0x3fcc422a, v116
	v_exp_f32_e32 v115, v115
	v_mul_f32_e32 v116, 0xbfb8aa3b, v116
	v_exp_f32_e32 v116, v116
	v_mul_f32_e32 v117, 0x3d372713, v112
	v_add_f32_e32 v115, 1.0, v115
	v_rcp_f32_e32 v118, v115
	v_add_f32_e32 v115, 1.0, v116
	v_mul_f32_e32 v116, 0x3d372713, v107
	v_mul_f32_e32 v119, 0x3d372713, v108
	v_mul_f32_e32 v116, v107, v116
	v_mul_f32_e32 v117, v112, v117
	v_mul_f32_e32 v119, v108, v119
	v_fma_f32 v116, v107, v116, v107
	v_fma_f32 v117, v112, v117, v112
	v_fma_f32 v119, v108, v119, v108
	v_mul_f32_e32 v116, 0x3fcc422a, v116
	v_mul_f32_e32 v117, 0x3fcc422a, v117
	v_mul_f32_e32 v119, 0x3fcc422a, v119
	v_mul_f32_e32 v116, 0xbfb8aa3b, v116
	v_mul_f32_e32 v117, 0xbfb8aa3b, v117
	v_mul_f32_e32 v119, 0xbfb8aa3b, v119
	v_exp_f32_e32 v116, v116
	v_exp_f32_e32 v117, v117
	v_exp_f32_e32 v119, v119
	v_mul_f32_e32 v114, 0x3d372713, v110
	v_add_f32_e32 v123, 1.0, v116
	v_add_f32_e32 v116, 1.0, v117
	v_add_f32_e32 v117, 1.0, v119
	v_mul_f32_e32 v119, 0x3d372713, v113
	v_mul_f32_e32 v120, 0x3d372713, v109
	v_mul_f32_e32 v114, v110, v114
	v_mul_f32_e32 v119, v113, v119
	v_mul_f32_e32 v120, v109, v120
	v_fma_f32 v114, v110, v114, v110
	v_fma_f32 v119, v113, v119, v113
	v_fma_f32 v120, v109, v120, v109
	v_mul_f32_e32 v114, 0x3fcc422a, v114
	v_mul_f32_e32 v119, 0x3fcc422a, v119
	v_mul_f32_e32 v120, 0x3fcc422a, v120
	v_mul_f32_e32 v114, 0xbfb8aa3b, v114
	v_mul_f32_e32 v119, 0xbfb8aa3b, v119
	v_mul_f32_e32 v120, 0xbfb8aa3b, v120
	v_exp_f32_e32 v114, v114
	v_exp_f32_e32 v119, v119
	v_exp_f32_e32 v121, v120
	v_rcp_f32_e32 v120, v117
	v_add_f32_e32 v114, 1.0, v114
	v_add_f32_e32 v117, 1.0, v119
	v_add_f32_e32 v119, 1.0, v121
	v_rcp_f32_e32 v114, v114
	v_rcp_f32_e32 v115, v115
	v_rcp_f32_e32 v116, v116
	v_rcp_f32_e32 v117, v117
	v_rcp_f32_e32 v121, v119
	v_rcp_f32_e32 v119, v123
	v_pk_mul_f32 v[114:115], v[110:111], v[114:115]
	v_pk_mul_f32 v[116:117], v[112:113], v[116:117]
	v_pk_mul_f32 v[120:121], v[108:109], v[120:121]
	v_pk_mul_f32 v[118:119], v[106:107], v[118:119]

.LBB0_381:
	v_or_b32_e32 v108, 32, v172
	v_mov_b64_e32 v[106:107], s[68:69]
	v_mad_i64_i32 v[106:107], s[0:1], v108, s9, v[106:107]
	v_lshl_add_u64 v[124:125], v[174:175], 1, v[106:107]
	v_cvt_pk_bf16_f32 v106, v114, v115
	v_cvt_pk_bf16_f32 v107, v116, v117
	v_cvt_pk_bf16_f32 v108, v118, v119
	v_cvt_pk_bf16_f32 v109, v120, v121
	global_store_dwordx4 v[124:125], v[106:109], off nt
	v_mov_b32_e32 v123, v122
	v_pk_fma_f32 v[102:103], v[122:123], v[102:103], v[54:55]
	v_mov_b32_e32 v106, v122
	v_mov_b32_e32 v107, v122
	v_pk_fma_f32 v[104:105], v[106:107], v[104:105], v[56:57]
	v_pk_fma_f32 v[100:101], v[106:107], v[100:101], v[52:53]
	v_pk_fma_f32 v[98:99], v[122:123], v[98:99], v[50:51]
	s_cmp_lt_i32 s16, 2
	s_mov_b64 s[14:15], -1
	s_cbranch_scc1 .LBB0_385
	v_mov_b64_e32 v[112:113], v[100:101]
	v_mov_b64_e32 v[108:109], v[104:105]
	s_cmp_eq_u32 s16, 2
	v_mov_b64_e32 v[110:111], v[98:99]
	v_mov_b64_e32 v[106:107], v[102:103]
	s_cbranch_scc0 .LBB0_384
	v_mul_f32_e32 v107, 0x3d372713, v98
	v_mul_f32_e32 v107, v98, v107
	v_mul_f32_e32 v108, 0x3d372713, v103
	v_fma_f32 v107, v98, v107, v98
	v_mul_f32_e32 v108, v103, v108
	v_mul_f32_e32 v107, 0x3fcc422a, v107
	v_fma_f32 v108, v103, v108, v103
	v_mul_f32_e32 v107, 0xbfb8aa3b, v107
	v_mul_f32_e32 v108, 0x3fcc422a, v108
	v_exp_f32_e32 v107, v107
	v_mul_f32_e32 v108, 0xbfb8aa3b, v108
	v_exp_f32_e32 v108, v108
	v_mul_f32_e32 v109, 0x3d372713, v104
	v_add_f32_e32 v107, 1.0, v107
	v_rcp_f32_e32 v110, v107
	v_add_f32_e32 v107, 1.0, v108
	v_mul_f32_e32 v108, 0x3d372713, v99
	v_mul_f32_e32 v111, 0x3d372713, v100
	v_mul_f32_e32 v108, v99, v108
	v_mul_f32_e32 v109, v104, v109
	v_mul_f32_e32 v111, v100, v111
	v_fma_f32 v108, v99, v108, v99
	v_fma_f32 v109, v104, v109, v104
	v_fma_f32 v111, v100, v111, v100
	v_mul_f32_e32 v108, 0x3fcc422a, v108
	v_mul_f32_e32 v109, 0x3fcc422a, v109
	v_mul_f32_e32 v111, 0x3fcc422a, v111
	v_mul_f32_e32 v108, 0xbfb8aa3b, v108
	v_mul_f32_e32 v109, 0xbfb8aa3b, v109
	v_mul_f32_e32 v111, 0xbfb8aa3b, v111
	v_exp_f32_e32 v108, v108
	v_exp_f32_e32 v109, v109
	v_exp_f32_e32 v111, v111
	v_mul_f32_e32 v106, 0x3d372713, v102
	v_add_f32_e32 v114, 1.0, v108
	v_add_f32_e32 v108, 1.0, v109
	v_add_f32_e32 v109, 1.0, v111
	v_mul_f32_e32 v111, 0x3d372713, v105
	v_mul_f32_e32 v112, 0x3d372713, v101
	v_mul_f32_e32 v106, v102, v106
	v_mul_f32_e32 v111, v105, v111
	v_mul_f32_e32 v112, v101, v112
	v_fma_f32 v106, v102, v106, v102
	v_fma_f32 v111, v105, v111, v105
	v_fma_f32 v112, v101, v112, v101
	v_mul_f32_e32 v106, 0x3fcc422a, v106
	v_mul_f32_e32 v111, 0x3fcc422a, v111
	v_mul_f32_e32 v112, 0x3fcc422a, v112
	v_mul_f32_e32 v106, 0xbfb8aa3b, v106
	v_mul_f32_e32 v111, 0xbfb8aa3b, v111
	v_mul_f32_e32 v112, 0xbfb8aa3b, v112
	v_exp_f32_e32 v106, v106
	v_exp_f32_e32 v111, v111
	v_exp_f32_e32 v113, v112
	v_rcp_f32_e32 v112, v109
	v_add_f32_e32 v106, 1.0, v106
	v_add_f32_e32 v109, 1.0, v111
	v_add_f32_e32 v111, 1.0, v113
	v_rcp_f32_e32 v106, v106
	v_rcp_f32_e32 v107, v107
	v_rcp_f32_e32 v108, v108
	v_rcp_f32_e32 v109, v109
	v_rcp_f32_e32 v113, v111
	v_rcp_f32_e32 v111, v114
	v_pk_mul_f32 v[106:107], v[102:103], v[106:107]
	v_pk_mul_f32 v[108:109], v[104:105], v[108:109]
	v_pk_mul_f32 v[112:113], v[100:101], v[112:113]
	v_pk_mul_f32 v[110:111], v[98:99], v[110:111]

.LBB0_389:
	v_cvt_pk_bf16_f32 v98, v106, v107
	v_cvt_pk_bf16_f32 v99, v108, v109
	v_cvt_pk_bf16_f32 v100, v110, v111
	v_cvt_pk_bf16_f32 v101, v112, v113
	global_store_dwordx4 v[124:125], v[98:101], off offset:256 nt
	s_cmp_lt_i32 s16, 2
	s_mov_b64 s[14:15], -1
	v_fmamk_f32 v98, v164, 0x3a800000, v235
	v_rsq_f32_e32 v106, v98
	s_nop 0
	v_pk_fma_f32 v[96:97], v[106:107], v[96:97], v[72:73] op_sel_hi:[0,1,1]
	v_pk_fma_f32 v[94:95], v[106:107], v[94:95], v[70:71] op_sel_hi:[0,1,1]
	v_pk_fma_f32 v[92:93], v[106:107], v[92:93], v[68:69] op_sel_hi:[0,1,1]
	v_pk_fma_f32 v[90:91], v[106:107], v[90:91], v[66:67] op_sel_hi:[0,1,1]
	s_cbranch_scc1 .LBB0_393
	v_mov_b64_e32 v[104:105], v[92:93]
	v_mov_b64_e32 v[100:101], v[96:97]
	s_cmp_eq_u32 s16, 2
	v_mov_b64_e32 v[102:103], v[90:91]
	v_mov_b64_e32 v[98:99], v[94:95]
	s_cbranch_scc0 .LBB0_392
	v_mul_f32_e32 v99, 0x3d372713, v90
	v_mul_f32_e32 v99, v90, v99
	v_mul_f32_e32 v100, 0x3d372713, v95
	v_fma_f32 v99, v90, v99, v90
	v_mul_f32_e32 v100, v95, v100
	v_mul_f32_e32 v99, 0x3fcc422a, v99
	v_fma_f32 v100, v95, v100, v95
	v_mul_f32_e32 v99, 0xbfb8aa3b, v99
	v_mul_f32_e32 v100, 0x3fcc422a, v100
	v_exp_f32_e32 v99, v99
	v_mul_f32_e32 v100, 0xbfb8aa3b, v100
	v_exp_f32_e32 v100, v100
	v_mul_f32_e32 v101, 0x3d372713, v96
	v_add_f32_e32 v99, 1.0, v99
	v_rcp_f32_e32 v102, v99
	v_add_f32_e32 v99, 1.0, v100
	v_mul_f32_e32 v100, 0x3d372713, v91
	v_mul_f32_e32 v103, 0x3d372713, v92
	v_mul_f32_e32 v100, v91, v100
	v_mul_f32_e32 v101, v96, v101
	v_mul_f32_e32 v103, v92, v103
	v_fma_f32 v100, v91, v100, v91
	v_fma_f32 v101, v96, v101, v96
	v_fma_f32 v103, v92, v103, v92
	v_mul_f32_e32 v100, 0x3fcc422a, v100
	v_mul_f32_e32 v101, 0x3fcc422a, v101
	v_mul_f32_e32 v103, 0x3fcc422a, v103
	v_mul_f32_e32 v100, 0xbfb8aa3b, v100
	v_mul_f32_e32 v101, 0xbfb8aa3b, v101
	v_mul_f32_e32 v103, 0xbfb8aa3b, v103
	v_exp_f32_e32 v100, v100
	v_exp_f32_e32 v101, v101
	v_exp_f32_e32 v103, v103
	v_mul_f32_e32 v98, 0x3d372713, v94
	v_add_f32_e32 v107, 1.0, v100
	v_add_f32_e32 v100, 1.0, v101
	v_add_f32_e32 v101, 1.0, v103
	v_mul_f32_e32 v103, 0x3d372713, v97
	v_mul_f32_e32 v104, 0x3d372713, v93
	v_mul_f32_e32 v98, v94, v98
	v_mul_f32_e32 v103, v97, v103
	v_mul_f32_e32 v104, v93, v104
	v_fma_f32 v98, v94, v98, v94
	v_fma_f32 v103, v97, v103, v97
	v_fma_f32 v104, v93, v104, v93
	v_mul_f32_e32 v98, 0x3fcc422a, v98
	v_mul_f32_e32 v103, 0x3fcc422a, v103
	v_mul_f32_e32 v104, 0x3fcc422a, v104
	v_mul_f32_e32 v98, 0xbfb8aa3b, v98
	v_mul_f32_e32 v103, 0xbfb8aa3b, v103
	v_mul_f32_e32 v104, 0xbfb8aa3b, v104
	v_exp_f32_e32 v98, v98
	v_exp_f32_e32 v103, v103
	v_exp_f32_e32 v105, v104
	v_rcp_f32_e32 v104, v101
	v_add_f32_e32 v98, 1.0, v98
	v_add_f32_e32 v101, 1.0, v103
	v_add_f32_e32 v103, 1.0, v105
	v_rcp_f32_e32 v98, v98
	v_rcp_f32_e32 v99, v99
	v_rcp_f32_e32 v100, v100
	v_rcp_f32_e32 v101, v101
	v_rcp_f32_e32 v105, v103
	v_rcp_f32_e32 v103, v107
	v_pk_mul_f32 v[98:99], v[94:95], v[98:99]
	v_pk_mul_f32 v[100:101], v[96:97], v[100:101]
	v_pk_mul_f32 v[104:105], v[92:93], v[104:105]
	v_pk_mul_f32 v[102:103], v[90:91], v[102:103]

.LBB0_397:
	v_or_b32_e32 v92, 48, v172
	v_mov_b64_e32 v[90:91], s[68:69]
	v_mad_i64_i32 v[90:91], s[0:1], v92, s9, v[90:91]
	v_lshl_add_u64 v[108:109], v[174:175], 1, v[90:91]
	v_cvt_pk_bf16_f32 v90, v98, v99
	v_cvt_pk_bf16_f32 v91, v100, v101
	v_cvt_pk_bf16_f32 v92, v102, v103
	v_cvt_pk_bf16_f32 v93, v104, v105
	global_store_dwordx4 v[108:109], v[90:93], off nt
	v_mov_b32_e32 v107, v106
	v_pk_fma_f32 v[86:87], v[106:107], v[86:87], v[54:55]
	v_mov_b32_e32 v90, v106
	v_mov_b32_e32 v91, v106
	v_pk_fma_f32 v[88:89], v[90:91], v[88:89], v[56:57]
	v_pk_fma_f32 v[84:85], v[90:91], v[84:85], v[52:53]
	v_pk_fma_f32 v[82:83], v[106:107], v[82:83], v[50:51]
	s_cmp_lt_i32 s16, 2
	s_mov_b64 s[14:15], -1
	s_cbranch_scc1 .LBB0_401
	v_mov_b64_e32 v[96:97], v[84:85]
	v_mov_b64_e32 v[92:93], v[88:89]
	s_cmp_eq_u32 s16, 2
	v_mov_b64_e32 v[94:95], v[82:83]
	v_mov_b64_e32 v[90:91], v[86:87]
	s_cbranch_scc0 .LBB0_400
	v_mul_f32_e32 v91, 0x3d372713, v82
	v_mul_f32_e32 v91, v82, v91
	v_mul_f32_e32 v92, 0x3d372713, v87
	v_fma_f32 v91, v82, v91, v82
	v_mul_f32_e32 v92, v87, v92
	v_mul_f32_e32 v91, 0x3fcc422a, v91
	v_fma_f32 v92, v87, v92, v87
	v_mul_f32_e32 v91, 0xbfb8aa3b, v91
	v_mul_f32_e32 v92, 0x3fcc422a, v92
	v_exp_f32_e32 v91, v91
	v_mul_f32_e32 v92, 0xbfb8aa3b, v92
	v_exp_f32_e32 v92, v92
	v_mul_f32_e32 v93, 0x3d372713, v88
	v_add_f32_e32 v91, 1.0, v91
	v_rcp_f32_e32 v94, v91
	v_add_f32_e32 v91, 1.0, v92
	v_mul_f32_e32 v92, 0x3d372713, v83
	v_mul_f32_e32 v95, 0x3d372713, v84
	v_mul_f32_e32 v92, v83, v92
	v_mul_f32_e32 v93, v88, v93
	v_mul_f32_e32 v95, v84, v95
	v_fma_f32 v92, v83, v92, v83
	v_fma_f32 v93, v88, v93, v88
	v_fma_f32 v95, v84, v95, v84
	v_mul_f32_e32 v92, 0x3fcc422a, v92
	v_mul_f32_e32 v93, 0x3fcc422a, v93
	v_mul_f32_e32 v95, 0x3fcc422a, v95
	v_mul_f32_e32 v92, 0xbfb8aa3b, v92
	v_mul_f32_e32 v93, 0xbfb8aa3b, v93
	v_mul_f32_e32 v95, 0xbfb8aa3b, v95
	v_exp_f32_e32 v92, v92
	v_exp_f32_e32 v93, v93
	v_exp_f32_e32 v95, v95
	v_mul_f32_e32 v90, 0x3d372713, v86
	v_add_f32_e32 v98, 1.0, v92
	v_add_f32_e32 v92, 1.0, v93
	v_add_f32_e32 v93, 1.0, v95
	v_mul_f32_e32 v95, 0x3d372713, v89
	v_mul_f32_e32 v96, 0x3d372713, v85
	v_mul_f32_e32 v90, v86, v90
	v_mul_f32_e32 v95, v89, v95
	v_mul_f32_e32 v96, v85, v96
	v_fma_f32 v90, v86, v90, v86
	v_fma_f32 v95, v89, v95, v89
	v_fma_f32 v96, v85, v96, v85
	v_mul_f32_e32 v90, 0x3fcc422a, v90
	v_mul_f32_e32 v95, 0x3fcc422a, v95
	v_mul_f32_e32 v96, 0x3fcc422a, v96
	v_mul_f32_e32 v90, 0xbfb8aa3b, v90
	v_mul_f32_e32 v95, 0xbfb8aa3b, v95
	v_mul_f32_e32 v96, 0xbfb8aa3b, v96
	v_exp_f32_e32 v90, v90
	v_exp_f32_e32 v95, v95
	v_exp_f32_e32 v97, v96
	v_rcp_f32_e32 v96, v93
	v_add_f32_e32 v90, 1.0, v90
	v_add_f32_e32 v93, 1.0, v95
	v_add_f32_e32 v95, 1.0, v97
	v_rcp_f32_e32 v90, v90
	v_rcp_f32_e32 v91, v91
	v_rcp_f32_e32 v92, v92
	v_rcp_f32_e32 v93, v93
	v_rcp_f32_e32 v97, v95
	v_rcp_f32_e32 v95, v98
	v_pk_mul_f32 v[90:91], v[86:87], v[90:91]
	v_pk_mul_f32 v[92:93], v[88:89], v[92:93]
	v_pk_mul_f32 v[96:97], v[84:85], v[96:97]
	v_pk_mul_f32 v[94:95], v[82:83], v[94:95]

.LBB0_405:
	v_cvt_pk_bf16_f32 v82, v90, v91
	v_cvt_pk_bf16_f32 v83, v92, v93
	v_cvt_pk_bf16_f32 v84, v94, v95
	v_cvt_pk_bf16_f32 v85, v96, v97
	global_store_dwordx4 v[108:109], v[82:85], off offset:256 nt
	s_cmp_lt_i32 s16, 2
	s_mov_b64 s[14:15], -1
	v_fmamk_f32 v82, v171, 0x3a800000, v235
	v_rsq_f32_e32 v90, v82
	s_nop 0
	v_pk_fma_f32 v[80:81], v[80:81], v[90:91], v[72:73] op_sel_hi:[1,0,1]
	v_pk_fma_f32 v[78:79], v[78:79], v[90:91], v[70:71] op_sel_hi:[1,0,1]
	v_pk_fma_f32 v[76:77], v[76:77], v[90:91], v[68:69] op_sel_hi:[1,0,1]
	v_pk_fma_f32 v[74:75], v[74:75], v[90:91], v[66:67] op_sel_hi:[1,0,1]
	s_cbranch_scc1 .LBB0_409
	v_mov_b64_e32 v[88:89], v[76:77]
	v_mov_b64_e32 v[84:85], v[80:81]
	s_cmp_eq_u32 s16, 2
	v_mov_b64_e32 v[86:87], v[74:75]
	v_mov_b64_e32 v[82:83], v[78:79]
	s_cbranch_scc0 .LBB0_408
	v_mul_f32_e32 v83, 0x3d372713, v74
	v_mul_f32_e32 v83, v74, v83
	v_mul_f32_e32 v84, 0x3d372713, v79
	v_fma_f32 v83, v74, v83, v74
	v_mul_f32_e32 v84, v79, v84
	v_mul_f32_e32 v83, 0x3fcc422a, v83
	v_fma_f32 v84, v79, v84, v79
	v_mul_f32_e32 v83, 0xbfb8aa3b, v83
	v_mul_f32_e32 v84, 0x3fcc422a, v84
	v_exp_f32_e32 v83, v83
	v_mul_f32_e32 v84, 0xbfb8aa3b, v84
	v_exp_f32_e32 v84, v84
	v_mul_f32_e32 v85, 0x3d372713, v80
	v_add_f32_e32 v83, 1.0, v83
	v_rcp_f32_e32 v86, v83
	v_add_f32_e32 v83, 1.0, v84
	v_mul_f32_e32 v84, 0x3d372713, v75
	v_mul_f32_e32 v87, 0x3d372713, v76
	v_mul_f32_e32 v84, v75, v84
	v_mul_f32_e32 v85, v80, v85
	v_mul_f32_e32 v87, v76, v87
	v_fma_f32 v84, v75, v84, v75
	v_fma_f32 v85, v80, v85, v80
	v_fma_f32 v87, v76, v87, v76
	v_mul_f32_e32 v84, 0x3fcc422a, v84
	v_mul_f32_e32 v85, 0x3fcc422a, v85
	v_mul_f32_e32 v87, 0x3fcc422a, v87
	v_mul_f32_e32 v84, 0xbfb8aa3b, v84
	v_mul_f32_e32 v85, 0xbfb8aa3b, v85
	v_mul_f32_e32 v87, 0xbfb8aa3b, v87
	v_exp_f32_e32 v84, v84
	v_exp_f32_e32 v85, v85
	v_exp_f32_e32 v87, v87
	v_mul_f32_e32 v82, 0x3d372713, v78
	v_add_f32_e32 v91, 1.0, v84
	v_add_f32_e32 v84, 1.0, v85
	v_add_f32_e32 v85, 1.0, v87
	v_mul_f32_e32 v87, 0x3d372713, v81
	v_mul_f32_e32 v88, 0x3d372713, v77
	v_mul_f32_e32 v82, v78, v82
	v_mul_f32_e32 v87, v81, v87
	v_mul_f32_e32 v88, v77, v88
	v_fma_f32 v82, v78, v82, v78
	v_fma_f32 v87, v81, v87, v81
	v_fma_f32 v88, v77, v88, v77
	v_mul_f32_e32 v82, 0x3fcc422a, v82
	v_mul_f32_e32 v87, 0x3fcc422a, v87
	v_mul_f32_e32 v88, 0x3fcc422a, v88
	v_mul_f32_e32 v82, 0xbfb8aa3b, v82
	v_mul_f32_e32 v87, 0xbfb8aa3b, v87
	v_mul_f32_e32 v88, 0xbfb8aa3b, v88
	v_exp_f32_e32 v82, v82
	v_exp_f32_e32 v87, v87
	v_exp_f32_e32 v89, v88
	v_rcp_f32_e32 v88, v85
	v_add_f32_e32 v82, 1.0, v82
	v_add_f32_e32 v85, 1.0, v87
	v_add_f32_e32 v87, 1.0, v89
	v_rcp_f32_e32 v82, v82
	v_rcp_f32_e32 v83, v83
	v_rcp_f32_e32 v84, v84
	v_rcp_f32_e32 v85, v85
	v_rcp_f32_e32 v89, v87
	v_rcp_f32_e32 v87, v91
	v_pk_mul_f32 v[82:83], v[78:79], v[82:83]
	v_pk_mul_f32 v[84:85], v[80:81], v[84:85]
	v_pk_mul_f32 v[88:89], v[76:77], v[88:89]
	v_pk_mul_f32 v[86:87], v[74:75], v[86:87]

.LBB0_413:
	v_mov_b64_e32 v[74:75], s[68:69]
	v_mad_i64_i32 v[74:75], s[0:1], v176, s9, v[74:75]
	v_lshl_add_u64 v[92:93], v[174:175], 1, v[74:75]
	v_cvt_pk_bf16_f32 v74, v82, v83
	v_cvt_pk_bf16_f32 v75, v84, v85
	v_cvt_pk_bf16_f32 v76, v86, v87
	v_cvt_pk_bf16_f32 v77, v88, v89
	global_store_dwordx4 v[92:93], v[74:77], off nt
	v_mov_b32_e32 v91, v90
	v_pk_fma_f32 v[62:63], v[62:63], v[90:91], v[54:55]
	v_mov_b32_e32 v74, v90
	v_mov_b32_e32 v75, v90
	v_pk_fma_f32 v[64:65], v[64:65], v[74:75], v[56:57]
	v_pk_fma_f32 v[60:61], v[60:61], v[74:75], v[52:53]
	v_pk_fma_f32 v[58:59], v[58:59], v[90:91], v[50:51]
	s_cmp_lt_i32 s16, 2
	s_mov_b64 s[14:15], -1
	s_cbranch_scc1 .LBB0_417
	v_mov_b64_e32 v[80:81], v[60:61]
	v_mov_b64_e32 v[76:77], v[64:65]
	s_cmp_eq_u32 s16, 2
	v_mov_b64_e32 v[78:79], v[58:59]
	v_mov_b64_e32 v[74:75], v[62:63]
	s_cbranch_scc0 .LBB0_416
	v_mul_f32_e32 v75, 0x3d372713, v58
	v_mul_f32_e32 v75, v58, v75
	v_mul_f32_e32 v76, 0x3d372713, v63
	v_fma_f32 v75, v58, v75, v58
	v_mul_f32_e32 v76, v63, v76
	v_mul_f32_e32 v75, 0x3fcc422a, v75
	v_fma_f32 v76, v63, v76, v63
	v_mul_f32_e32 v75, 0xbfb8aa3b, v75
	v_mul_f32_e32 v76, 0x3fcc422a, v76
	v_exp_f32_e32 v75, v75
	v_mul_f32_e32 v76, 0xbfb8aa3b, v76
	v_exp_f32_e32 v76, v76
	v_mul_f32_e32 v77, 0x3d372713, v64
	v_add_f32_e32 v75, 1.0, v75
	v_rcp_f32_e32 v78, v75
	v_add_f32_e32 v75, 1.0, v76
	v_mul_f32_e32 v76, 0x3d372713, v59
	v_mul_f32_e32 v79, 0x3d372713, v60
	v_mul_f32_e32 v76, v59, v76
	v_mul_f32_e32 v77, v64, v77
	v_mul_f32_e32 v79, v60, v79
	v_fma_f32 v76, v59, v76, v59
	v_fma_f32 v77, v64, v77, v64
	v_fma_f32 v79, v60, v79, v60
	v_mul_f32_e32 v76, 0x3fcc422a, v76
	v_mul_f32_e32 v77, 0x3fcc422a, v77
	v_mul_f32_e32 v79, 0x3fcc422a, v79
	v_mul_f32_e32 v76, 0xbfb8aa3b, v76
	v_mul_f32_e32 v77, 0xbfb8aa3b, v77
	v_mul_f32_e32 v79, 0xbfb8aa3b, v79
	v_exp_f32_e32 v76, v76
	v_exp_f32_e32 v77, v77
	v_exp_f32_e32 v79, v79
	v_mul_f32_e32 v74, 0x3d372713, v62
	v_add_f32_e32 v82, 1.0, v76
	v_add_f32_e32 v76, 1.0, v77
	v_add_f32_e32 v77, 1.0, v79
	v_mul_f32_e32 v79, 0x3d372713, v65
	v_mul_f32_e32 v80, 0x3d372713, v61
	v_mul_f32_e32 v74, v62, v74
	v_mul_f32_e32 v79, v65, v79
	v_mul_f32_e32 v80, v61, v80
	v_fma_f32 v74, v62, v74, v62
	v_fma_f32 v79, v65, v79, v65
	v_fma_f32 v80, v61, v80, v61
	v_mul_f32_e32 v74, 0x3fcc422a, v74
	v_mul_f32_e32 v79, 0x3fcc422a, v79
	v_mul_f32_e32 v80, 0x3fcc422a, v80
	v_mul_f32_e32 v74, 0xbfb8aa3b, v74
	v_mul_f32_e32 v79, 0xbfb8aa3b, v79
	v_mul_f32_e32 v80, 0xbfb8aa3b, v80
	v_exp_f32_e32 v74, v74
	v_exp_f32_e32 v79, v79
	v_exp_f32_e32 v81, v80
	v_rcp_f32_e32 v80, v77
	v_add_f32_e32 v74, 1.0, v74
	v_add_f32_e32 v77, 1.0, v79
	v_add_f32_e32 v79, 1.0, v81
	v_rcp_f32_e32 v74, v74
	v_rcp_f32_e32 v75, v75
	v_rcp_f32_e32 v76, v76
	v_rcp_f32_e32 v77, v77
	v_rcp_f32_e32 v81, v79
	v_rcp_f32_e32 v79, v82
	v_pk_mul_f32 v[74:75], v[62:63], v[74:75]
	v_pk_mul_f32 v[76:77], v[64:65], v[76:77]
	v_pk_mul_f32 v[80:81], v[60:61], v[80:81]
	v_pk_mul_f32 v[78:79], v[58:59], v[78:79]

.LBB0_421:
	v_cvt_pk_bf16_f32 v58, v74, v75
	v_cvt_pk_bf16_f32 v59, v76, v77
	v_cvt_pk_bf16_f32 v60, v78, v79
	v_cvt_pk_bf16_f32 v61, v80, v81
	global_store_dwordx4 v[92:93], v[58:61], off offset:256 nt
	s_cmp_lt_i32 s16, 2
	s_mov_b64 s[14:15], -1
	v_fmamk_f32 v58, v169, 0x3a800000, v235
	v_rsq_f32_e32 v74, v58
	s_nop 0
	v_pk_fma_f32 v[48:49], v[48:49], v[74:75], v[72:73] op_sel_hi:[1,0,1]
	v_pk_fma_f32 v[46:47], v[46:47], v[74:75], v[70:71] op_sel_hi:[1,0,1]
	v_pk_fma_f32 v[44:45], v[44:45], v[74:75], v[68:69] op_sel_hi:[1,0,1]
	v_pk_fma_f32 v[42:43], v[42:43], v[74:75], v[66:67] op_sel_hi:[1,0,1]
	s_cbranch_scc1 .LBB0_425
	v_mov_b64_e32 v[64:65], v[44:45]
	v_mov_b64_e32 v[60:61], v[48:49]
	s_cmp_eq_u32 s16, 2
	v_mov_b64_e32 v[62:63], v[42:43]
	v_mov_b64_e32 v[58:59], v[46:47]
	s_cbranch_scc0 .LBB0_424
	v_mul_f32_e32 v59, 0x3d372713, v42
	v_mul_f32_e32 v59, v42, v59
	v_mul_f32_e32 v60, 0x3d372713, v47
	v_fma_f32 v59, v42, v59, v42
	v_mul_f32_e32 v60, v47, v60
	v_mul_f32_e32 v59, 0x3fcc422a, v59
	v_fma_f32 v60, v47, v60, v47
	v_mul_f32_e32 v59, 0xbfb8aa3b, v59
	v_mul_f32_e32 v60, 0x3fcc422a, v60
	v_exp_f32_e32 v59, v59
	v_mul_f32_e32 v60, 0xbfb8aa3b, v60
	v_exp_f32_e32 v60, v60
	v_mul_f32_e32 v61, 0x3d372713, v48
	v_add_f32_e32 v59, 1.0, v59
	v_rcp_f32_e32 v62, v59
	v_add_f32_e32 v59, 1.0, v60
	v_mul_f32_e32 v60, 0x3d372713, v43
	v_mul_f32_e32 v63, 0x3d372713, v44
	v_mul_f32_e32 v60, v43, v60
	v_mul_f32_e32 v61, v48, v61
	v_mul_f32_e32 v63, v44, v63
	v_fma_f32 v60, v43, v60, v43
	v_fma_f32 v61, v48, v61, v48
	v_fma_f32 v63, v44, v63, v44
	v_mul_f32_e32 v60, 0x3fcc422a, v60
	v_mul_f32_e32 v61, 0x3fcc422a, v61
	v_mul_f32_e32 v63, 0x3fcc422a, v63
	v_mul_f32_e32 v60, 0xbfb8aa3b, v60
	v_mul_f32_e32 v61, 0xbfb8aa3b, v61
	v_mul_f32_e32 v63, 0xbfb8aa3b, v63
	v_exp_f32_e32 v60, v60
	v_exp_f32_e32 v61, v61
	v_exp_f32_e32 v63, v63
	v_mul_f32_e32 v58, 0x3d372713, v46
	v_add_f32_e32 v75, 1.0, v60
	v_add_f32_e32 v60, 1.0, v61
	v_add_f32_e32 v61, 1.0, v63
	v_mul_f32_e32 v63, 0x3d372713, v49
	v_mul_f32_e32 v64, 0x3d372713, v45
	v_mul_f32_e32 v58, v46, v58
	v_mul_f32_e32 v63, v49, v63
	v_mul_f32_e32 v64, v45, v64
	v_fma_f32 v58, v46, v58, v46
	v_fma_f32 v63, v49, v63, v49
	v_fma_f32 v64, v45, v64, v45
	v_mul_f32_e32 v58, 0x3fcc422a, v58
	v_mul_f32_e32 v63, 0x3fcc422a, v63
	v_mul_f32_e32 v64, 0x3fcc422a, v64
	v_mul_f32_e32 v58, 0xbfb8aa3b, v58
	v_mul_f32_e32 v63, 0xbfb8aa3b, v63
	v_mul_f32_e32 v64, 0xbfb8aa3b, v64
	v_exp_f32_e32 v58, v58
	v_exp_f32_e32 v63, v63
	v_exp_f32_e32 v65, v64
	v_rcp_f32_e32 v64, v61
	v_add_f32_e32 v58, 1.0, v58
	v_add_f32_e32 v61, 1.0, v63
	v_add_f32_e32 v63, 1.0, v65
	v_rcp_f32_e32 v58, v58
	v_rcp_f32_e32 v59, v59
	v_rcp_f32_e32 v60, v60
	v_rcp_f32_e32 v61, v61
	v_rcp_f32_e32 v65, v63
	v_rcp_f32_e32 v63, v75
	v_pk_mul_f32 v[58:59], v[46:47], v[58:59]
	v_pk_mul_f32 v[60:61], v[48:49], v[60:61]
	v_pk_mul_f32 v[64:65], v[44:45], v[64:65]
	v_pk_mul_f32 v[62:63], v[42:43], v[62:63]

.LBB0_429:
	v_add_u32_e32 v44, 0x90, v172
	v_mov_b64_e32 v[42:43], s[68:69]
	v_mad_i64_i32 v[42:43], s[0:1], v44, s9, v[42:43]
	v_lshl_add_u64 v[76:77], v[174:175], 1, v[42:43]
	v_cvt_pk_bf16_f32 v42, v58, v59
	v_cvt_pk_bf16_f32 v43, v60, v61
	v_cvt_pk_bf16_f32 v44, v62, v63
	v_cvt_pk_bf16_f32 v45, v64, v65
	global_store_dwordx4 v[76:77], v[42:45], off nt
	v_mov_b32_e32 v75, v74
	v_pk_fma_f32 v[38:39], v[38:39], v[74:75], v[54:55]
	v_mov_b32_e32 v42, v74
	v_mov_b32_e32 v43, v74
	v_pk_fma_f32 v[40:41], v[40:41], v[42:43], v[56:57]
	v_pk_fma_f32 v[36:37], v[36:37], v[42:43], v[52:53]
	v_pk_fma_f32 v[34:35], v[34:35], v[74:75], v[50:51]
	s_cmp_lt_i32 s16, 2
	s_mov_b64 s[14:15], -1
	s_cbranch_scc1 .LBB0_433
	v_mov_b64_e32 v[48:49], v[36:37]
	v_mov_b64_e32 v[44:45], v[40:41]
	s_cmp_eq_u32 s16, 2
	v_mov_b64_e32 v[46:47], v[34:35]
	v_mov_b64_e32 v[42:43], v[38:39]
	s_cbranch_scc0 .LBB0_432
	v_mul_f32_e32 v43, 0x3d372713, v34
	v_mul_f32_e32 v43, v34, v43
	v_mul_f32_e32 v44, 0x3d372713, v39
	v_fma_f32 v43, v34, v43, v34
	v_mul_f32_e32 v44, v39, v44
	v_mul_f32_e32 v43, 0x3fcc422a, v43
	v_fma_f32 v44, v39, v44, v39
	v_mul_f32_e32 v43, 0xbfb8aa3b, v43
	v_mul_f32_e32 v44, 0x3fcc422a, v44
	v_exp_f32_e32 v43, v43
	v_mul_f32_e32 v44, 0xbfb8aa3b, v44
	v_exp_f32_e32 v44, v44
	v_mul_f32_e32 v45, 0x3d372713, v40
	v_add_f32_e32 v43, 1.0, v43
	v_rcp_f32_e32 v46, v43
	v_add_f32_e32 v43, 1.0, v44
	v_mul_f32_e32 v44, 0x3d372713, v35
	v_mul_f32_e32 v47, 0x3d372713, v36
	v_mul_f32_e32 v44, v35, v44
	v_mul_f32_e32 v45, v40, v45
	v_mul_f32_e32 v47, v36, v47
	v_fma_f32 v44, v35, v44, v35
	v_fma_f32 v45, v40, v45, v40
	v_fma_f32 v47, v36, v47, v36
	v_mul_f32_e32 v44, 0x3fcc422a, v44
	v_mul_f32_e32 v45, 0x3fcc422a, v45
	v_mul_f32_e32 v47, 0x3fcc422a, v47
	v_mul_f32_e32 v44, 0xbfb8aa3b, v44
	v_mul_f32_e32 v45, 0xbfb8aa3b, v45
	v_mul_f32_e32 v47, 0xbfb8aa3b, v47
	v_exp_f32_e32 v44, v44
	v_exp_f32_e32 v45, v45
	v_exp_f32_e32 v47, v47
	v_mul_f32_e32 v42, 0x3d372713, v38
	v_add_f32_e32 v58, 1.0, v44
	v_add_f32_e32 v44, 1.0, v45
	v_add_f32_e32 v45, 1.0, v47
	v_mul_f32_e32 v47, 0x3d372713, v41
	v_mul_f32_e32 v48, 0x3d372713, v37
	v_mul_f32_e32 v42, v38, v42
	v_mul_f32_e32 v47, v41, v47
	v_mul_f32_e32 v48, v37, v48
	v_fma_f32 v42, v38, v42, v38
	v_fma_f32 v47, v41, v47, v41
	v_fma_f32 v48, v37, v48, v37
	v_mul_f32_e32 v42, 0x3fcc422a, v42
	v_mul_f32_e32 v47, 0x3fcc422a, v47
	v_mul_f32_e32 v48, 0x3fcc422a, v48
	v_mul_f32_e32 v42, 0xbfb8aa3b, v42
	v_mul_f32_e32 v47, 0xbfb8aa3b, v47
	v_mul_f32_e32 v48, 0xbfb8aa3b, v48
	v_exp_f32_e32 v42, v42
	v_exp_f32_e32 v47, v47
	v_exp_f32_e32 v49, v48
	v_rcp_f32_e32 v48, v45
	v_add_f32_e32 v42, 1.0, v42
	v_add_f32_e32 v45, 1.0, v47
	v_add_f32_e32 v47, 1.0, v49
	v_rcp_f32_e32 v42, v42
	v_rcp_f32_e32 v43, v43
	v_rcp_f32_e32 v44, v44
	v_rcp_f32_e32 v45, v45
	v_rcp_f32_e32 v49, v47
	v_rcp_f32_e32 v47, v58
	v_pk_mul_f32 v[42:43], v[38:39], v[42:43]
	v_pk_mul_f32 v[44:45], v[40:41], v[44:45]
	v_pk_mul_f32 v[48:49], v[36:37], v[48:49]
	v_pk_mul_f32 v[46:47], v[34:35], v[46:47]

.LBB0_437:
	v_cvt_pk_bf16_f32 v34, v42, v43
	v_cvt_pk_bf16_f32 v35, v44, v45
	v_cvt_pk_bf16_f32 v36, v46, v47
	v_cvt_pk_bf16_f32 v37, v48, v49
	global_store_dwordx4 v[76:77], v[34:37], off offset:256 nt
	s_cmp_lt_i32 s16, 2
	s_mov_b64 s[14:15], -1
	v_fmamk_f32 v34, v167, 0x3a800000, v235
	v_rsq_f32_e32 v42, v34
	s_nop 0
	v_pk_fma_f32 v[32:33], v[32:33], v[42:43], v[72:73] op_sel_hi:[1,0,1]
	v_pk_fma_f32 v[30:31], v[30:31], v[42:43], v[70:71] op_sel_hi:[1,0,1]
	v_pk_fma_f32 v[28:29], v[28:29], v[42:43], v[68:69] op_sel_hi:[1,0,1]
	v_pk_fma_f32 v[26:27], v[26:27], v[42:43], v[66:67] op_sel_hi:[1,0,1]
	s_cbranch_scc1 .LBB0_441
	v_mov_b64_e32 v[40:41], v[28:29]
	v_mov_b64_e32 v[36:37], v[32:33]
	s_cmp_eq_u32 s16, 2
	v_mov_b64_e32 v[38:39], v[26:27]
	v_mov_b64_e32 v[34:35], v[30:31]
	s_cbranch_scc0 .LBB0_440
	v_mul_f32_e32 v35, 0x3d372713, v26
	v_mul_f32_e32 v35, v26, v35
	v_mul_f32_e32 v36, 0x3d372713, v31
	v_fma_f32 v35, v26, v35, v26
	v_mul_f32_e32 v36, v31, v36
	v_mul_f32_e32 v35, 0x3fcc422a, v35
	v_fma_f32 v36, v31, v36, v31
	v_mul_f32_e32 v35, 0xbfb8aa3b, v35
	v_mul_f32_e32 v36, 0x3fcc422a, v36
	v_exp_f32_e32 v35, v35
	v_mul_f32_e32 v36, 0xbfb8aa3b, v36
	v_exp_f32_e32 v36, v36
	v_mul_f32_e32 v37, 0x3d372713, v32
	v_add_f32_e32 v35, 1.0, v35
	v_rcp_f32_e32 v38, v35
	v_add_f32_e32 v35, 1.0, v36
	v_mul_f32_e32 v36, 0x3d372713, v27
	v_mul_f32_e32 v39, 0x3d372713, v28
	v_mul_f32_e32 v36, v27, v36
	v_mul_f32_e32 v37, v32, v37
	v_mul_f32_e32 v39, v28, v39
	v_fma_f32 v36, v27, v36, v27
	v_fma_f32 v37, v32, v37, v32
	v_fma_f32 v39, v28, v39, v28
	v_mul_f32_e32 v36, 0x3fcc422a, v36
	v_mul_f32_e32 v37, 0x3fcc422a, v37
	v_mul_f32_e32 v39, 0x3fcc422a, v39
	v_mul_f32_e32 v36, 0xbfb8aa3b, v36
	v_mul_f32_e32 v37, 0xbfb8aa3b, v37
	v_mul_f32_e32 v39, 0xbfb8aa3b, v39
	v_exp_f32_e32 v36, v36
	v_exp_f32_e32 v37, v37
	v_exp_f32_e32 v39, v39
	v_mul_f32_e32 v34, 0x3d372713, v30
	v_add_f32_e32 v43, 1.0, v36
	v_add_f32_e32 v36, 1.0, v37
	v_add_f32_e32 v37, 1.0, v39
	v_mul_f32_e32 v39, 0x3d372713, v33
	v_mul_f32_e32 v40, 0x3d372713, v29
	v_mul_f32_e32 v34, v30, v34
	v_mul_f32_e32 v39, v33, v39
	v_mul_f32_e32 v40, v29, v40
	v_fma_f32 v34, v30, v34, v30
	v_fma_f32 v39, v33, v39, v33
	v_fma_f32 v40, v29, v40, v29
	v_mul_f32_e32 v34, 0x3fcc422a, v34
	v_mul_f32_e32 v39, 0x3fcc422a, v39
	v_mul_f32_e32 v40, 0x3fcc422a, v40
	v_mul_f32_e32 v34, 0xbfb8aa3b, v34
	v_mul_f32_e32 v39, 0xbfb8aa3b, v39
	v_mul_f32_e32 v40, 0xbfb8aa3b, v40
	v_exp_f32_e32 v34, v34
	v_exp_f32_e32 v39, v39
	v_exp_f32_e32 v41, v40
	v_rcp_f32_e32 v40, v37
	v_add_f32_e32 v34, 1.0, v34
	v_add_f32_e32 v37, 1.0, v39
	v_add_f32_e32 v39, 1.0, v41
	v_rcp_f32_e32 v34, v34
	v_rcp_f32_e32 v35, v35
	v_rcp_f32_e32 v36, v36
	v_rcp_f32_e32 v37, v37
	v_rcp_f32_e32 v41, v39
	v_rcp_f32_e32 v39, v43
	v_pk_mul_f32 v[34:35], v[30:31], v[34:35]
	v_pk_mul_f32 v[36:37], v[32:33], v[36:37]
	v_pk_mul_f32 v[40:41], v[28:29], v[40:41]
	v_pk_mul_f32 v[38:39], v[26:27], v[38:39]

.LBB0_445:
	v_add_u32_e32 v28, 0xa0, v172
	v_mov_b64_e32 v[26:27], s[68:69]
	v_mad_i64_i32 v[26:27], s[0:1], v28, s9, v[26:27]
	v_lshl_add_u64 v[44:45], v[174:175], 1, v[26:27]
	v_cvt_pk_bf16_f32 v26, v34, v35
	v_cvt_pk_bf16_f32 v27, v36, v37
	v_cvt_pk_bf16_f32 v28, v38, v39
	v_cvt_pk_bf16_f32 v29, v40, v41
	global_store_dwordx4 v[44:45], v[26:29], off nt
	v_mov_b32_e32 v43, v42
	v_pk_fma_f32 v[22:23], v[22:23], v[42:43], v[54:55]
	v_mov_b32_e32 v26, v42
	v_mov_b32_e32 v27, v42
	v_pk_fma_f32 v[24:25], v[24:25], v[26:27], v[56:57]
	v_pk_fma_f32 v[20:21], v[20:21], v[26:27], v[52:53]
	v_pk_fma_f32 v[18:19], v[18:19], v[42:43], v[50:51]
	s_cmp_lt_i32 s16, 2
	s_mov_b64 s[14:15], -1
	s_cbranch_scc1 .LBB0_449
	v_mov_b64_e32 v[32:33], v[20:21]
	v_mov_b64_e32 v[28:29], v[24:25]
	s_cmp_eq_u32 s16, 2
	v_mov_b64_e32 v[30:31], v[18:19]
	v_mov_b64_e32 v[26:27], v[22:23]
	s_cbranch_scc0 .LBB0_448
	v_mul_f32_e32 v27, 0x3d372713, v18
	v_mul_f32_e32 v27, v18, v27
	v_mul_f32_e32 v28, 0x3d372713, v23
	v_fma_f32 v27, v18, v27, v18
	v_mul_f32_e32 v28, v23, v28
	v_mul_f32_e32 v27, 0x3fcc422a, v27
	v_fma_f32 v28, v23, v28, v23
	v_mul_f32_e32 v27, 0xbfb8aa3b, v27
	v_mul_f32_e32 v28, 0x3fcc422a, v28
	v_exp_f32_e32 v27, v27
	v_mul_f32_e32 v28, 0xbfb8aa3b, v28
	v_exp_f32_e32 v28, v28
	v_mul_f32_e32 v29, 0x3d372713, v24
	v_add_f32_e32 v27, 1.0, v27
	v_rcp_f32_e32 v30, v27
	v_add_f32_e32 v27, 1.0, v28
	v_mul_f32_e32 v28, 0x3d372713, v19
	v_mul_f32_e32 v31, 0x3d372713, v20
	v_mul_f32_e32 v28, v19, v28
	v_mul_f32_e32 v29, v24, v29
	v_mul_f32_e32 v31, v20, v31
	v_fma_f32 v28, v19, v28, v19
	v_fma_f32 v29, v24, v29, v24
	v_fma_f32 v31, v20, v31, v20
	v_mul_f32_e32 v28, 0x3fcc422a, v28
	v_mul_f32_e32 v29, 0x3fcc422a, v29
	v_mul_f32_e32 v31, 0x3fcc422a, v31
	v_mul_f32_e32 v28, 0xbfb8aa3b, v28
	v_mul_f32_e32 v29, 0xbfb8aa3b, v29
	v_mul_f32_e32 v31, 0xbfb8aa3b, v31
	v_exp_f32_e32 v28, v28
	v_exp_f32_e32 v29, v29
	v_exp_f32_e32 v31, v31
	v_mul_f32_e32 v26, 0x3d372713, v22
	v_add_f32_e32 v34, 1.0, v28
	v_add_f32_e32 v28, 1.0, v29
	v_add_f32_e32 v29, 1.0, v31
	v_mul_f32_e32 v31, 0x3d372713, v25
	v_mul_f32_e32 v32, 0x3d372713, v21
	v_mul_f32_e32 v26, v22, v26
	v_mul_f32_e32 v31, v25, v31
	v_mul_f32_e32 v32, v21, v32
	v_fma_f32 v26, v22, v26, v22
	v_fma_f32 v31, v25, v31, v25
	v_fma_f32 v32, v21, v32, v21
	v_mul_f32_e32 v26, 0x3fcc422a, v26
	v_mul_f32_e32 v31, 0x3fcc422a, v31
	v_mul_f32_e32 v32, 0x3fcc422a, v32
	v_mul_f32_e32 v26, 0xbfb8aa3b, v26
	v_mul_f32_e32 v31, 0xbfb8aa3b, v31
	v_mul_f32_e32 v32, 0xbfb8aa3b, v32
	v_exp_f32_e32 v26, v26
	v_exp_f32_e32 v31, v31
	v_exp_f32_e32 v33, v32
	v_rcp_f32_e32 v32, v29
	v_add_f32_e32 v26, 1.0, v26
	v_add_f32_e32 v29, 1.0, v31
	v_add_f32_e32 v31, 1.0, v33
	v_rcp_f32_e32 v26, v26
	v_rcp_f32_e32 v27, v27
	v_rcp_f32_e32 v28, v28
	v_rcp_f32_e32 v29, v29
	v_rcp_f32_e32 v33, v31
	v_rcp_f32_e32 v31, v34
	v_pk_mul_f32 v[26:27], v[22:23], v[26:27]
	v_pk_mul_f32 v[28:29], v[24:25], v[28:29]
	v_pk_mul_f32 v[32:33], v[20:21], v[32:33]
	v_pk_mul_f32 v[30:31], v[18:19], v[30:31]

.LBB0_453:
	v_cvt_pk_bf16_f32 v18, v26, v27
	v_cvt_pk_bf16_f32 v19, v28, v29
	v_cvt_pk_bf16_f32 v20, v30, v31
	v_cvt_pk_bf16_f32 v21, v32, v33
	global_store_dwordx4 v[44:45], v[18:21], off offset:256 nt
	s_cmp_lt_i32 s16, 2
	s_mov_b64 s[14:15], -1
	v_fmamk_f32 v18, v165, 0x3a800000, v235
	v_rsq_f32_e32 v26, v18
	s_nop 0
	v_pk_fma_f32 v[16:17], v[16:17], v[26:27], v[72:73] op_sel_hi:[1,0,1]
	v_pk_fma_f32 v[14:15], v[14:15], v[26:27], v[70:71] op_sel_hi:[1,0,1]
	v_pk_fma_f32 v[12:13], v[12:13], v[26:27], v[68:69] op_sel_hi:[1,0,1]
	v_pk_fma_f32 v[10:11], v[10:11], v[26:27], v[66:67] op_sel_hi:[1,0,1]
	s_cbranch_scc1 .LBB0_457
	v_mov_b64_e32 v[24:25], v[12:13]
	v_mov_b64_e32 v[20:21], v[16:17]
	s_cmp_eq_u32 s16, 2
	v_mov_b64_e32 v[22:23], v[10:11]
	v_mov_b64_e32 v[18:19], v[14:15]
	s_cbranch_scc0 .LBB0_456
	v_mul_f32_e32 v19, 0x3d372713, v10
	v_mul_f32_e32 v19, v10, v19
	v_mul_f32_e32 v20, 0x3d372713, v15
	v_fma_f32 v19, v10, v19, v10
	v_mul_f32_e32 v20, v15, v20
	v_mul_f32_e32 v19, 0x3fcc422a, v19
	v_fma_f32 v20, v15, v20, v15
	v_mul_f32_e32 v19, 0xbfb8aa3b, v19
	v_mul_f32_e32 v20, 0x3fcc422a, v20
	v_exp_f32_e32 v19, v19
	v_mul_f32_e32 v20, 0xbfb8aa3b, v20
	v_exp_f32_e32 v20, v20
	v_mul_f32_e32 v21, 0x3d372713, v16
	v_add_f32_e32 v19, 1.0, v19
	v_rcp_f32_e32 v22, v19
	v_add_f32_e32 v19, 1.0, v20
	v_mul_f32_e32 v20, 0x3d372713, v11
	v_mul_f32_e32 v23, 0x3d372713, v12
	v_mul_f32_e32 v20, v11, v20
	v_mul_f32_e32 v21, v16, v21
	v_mul_f32_e32 v23, v12, v23
	v_fma_f32 v20, v11, v20, v11
	v_fma_f32 v21, v16, v21, v16
	v_fma_f32 v23, v12, v23, v12
	v_mul_f32_e32 v20, 0x3fcc422a, v20
	v_mul_f32_e32 v21, 0x3fcc422a, v21
	v_mul_f32_e32 v23, 0x3fcc422a, v23
	v_mul_f32_e32 v20, 0xbfb8aa3b, v20
	v_mul_f32_e32 v21, 0xbfb8aa3b, v21
	v_mul_f32_e32 v23, 0xbfb8aa3b, v23
	v_exp_f32_e32 v20, v20
	v_exp_f32_e32 v21, v21
	v_exp_f32_e32 v23, v23
	v_mul_f32_e32 v18, 0x3d372713, v14
	v_add_f32_e32 v27, 1.0, v20
	v_add_f32_e32 v20, 1.0, v21
	v_add_f32_e32 v21, 1.0, v23
	v_mul_f32_e32 v23, 0x3d372713, v17
	v_mul_f32_e32 v24, 0x3d372713, v13
	v_mul_f32_e32 v18, v14, v18
	v_mul_f32_e32 v23, v17, v23
	v_mul_f32_e32 v24, v13, v24
	v_fma_f32 v18, v14, v18, v14
	v_fma_f32 v23, v17, v23, v17
	v_fma_f32 v24, v13, v24, v13
	v_mul_f32_e32 v18, 0x3fcc422a, v18
	v_mul_f32_e32 v23, 0x3fcc422a, v23
	v_mul_f32_e32 v24, 0x3fcc422a, v24
	v_mul_f32_e32 v18, 0xbfb8aa3b, v18
	v_mul_f32_e32 v23, 0xbfb8aa3b, v23
	v_mul_f32_e32 v24, 0xbfb8aa3b, v24
	v_exp_f32_e32 v18, v18
	v_exp_f32_e32 v23, v23
	v_exp_f32_e32 v25, v24
	v_rcp_f32_e32 v24, v21
	v_add_f32_e32 v18, 1.0, v18
	v_add_f32_e32 v21, 1.0, v23
	v_add_f32_e32 v23, 1.0, v25
	v_rcp_f32_e32 v18, v18
	v_rcp_f32_e32 v19, v19
	v_rcp_f32_e32 v20, v20
	v_rcp_f32_e32 v21, v21
	v_rcp_f32_e32 v25, v23
	v_rcp_f32_e32 v23, v27
	v_pk_mul_f32 v[18:19], v[14:15], v[18:19]
	v_pk_mul_f32 v[20:21], v[16:17], v[20:21]
	v_pk_mul_f32 v[24:25], v[12:13], v[24:25]
	v_pk_mul_f32 v[22:23], v[10:11], v[22:23]

.LBB0_461:
	v_add_u32_e32 v12, 0xb0, v172
	v_mov_b64_e32 v[10:11], s[68:69]
	v_mad_i64_i32 v[10:11], s[0:1], v12, s9, v[10:11]
	v_lshl_add_u64 v[66:67], v[174:175], 1, v[10:11]
	v_cvt_pk_bf16_f32 v10, v18, v19
	v_cvt_pk_bf16_f32 v11, v20, v21
	v_cvt_pk_bf16_f32 v12, v22, v23
	v_cvt_pk_bf16_f32 v13, v24, v25
	global_store_dwordx4 v[66:67], v[10:13], off nt
	v_mov_b32_e32 v27, v26
	v_pk_fma_f32 v[6:7], v[6:7], v[26:27], v[54:55]
	v_mov_b32_e32 v10, v26
	v_mov_b32_e32 v11, v26
	v_pk_fma_f32 v[8:9], v[8:9], v[10:11], v[56:57]
	v_pk_fma_f32 v[4:5], v[4:5], v[10:11], v[52:53]
	v_pk_fma_f32 v[2:3], v[2:3], v[26:27], v[50:51]
	s_cmp_lt_i32 s16, 2
	s_mov_b64 s[14:15], -1
	s_cbranch_scc1 .LBB0_465
	v_mov_b64_e32 v[16:17], v[4:5]
	v_mov_b64_e32 v[12:13], v[8:9]
	s_cmp_eq_u32 s16, 2
	v_mov_b64_e32 v[14:15], v[2:3]
	v_mov_b64_e32 v[10:11], v[6:7]
	s_cbranch_scc0 .LBB0_464
	v_mul_f32_e32 v11, 0x3d372713, v2
	v_mul_f32_e32 v11, v2, v11
	v_mul_f32_e32 v12, 0x3d372713, v7
	v_fma_f32 v11, v2, v11, v2
	v_mul_f32_e32 v12, v7, v12
	v_mul_f32_e32 v11, 0x3fcc422a, v11
	v_fma_f32 v12, v7, v12, v7
	v_mul_f32_e32 v11, 0xbfb8aa3b, v11
	v_mul_f32_e32 v12, 0x3fcc422a, v12
	v_exp_f32_e32 v11, v11
	v_mul_f32_e32 v12, 0xbfb8aa3b, v12
	v_exp_f32_e32 v12, v12
	v_mul_f32_e32 v13, 0x3d372713, v8
	v_add_f32_e32 v11, 1.0, v11
	v_rcp_f32_e32 v14, v11
	v_add_f32_e32 v11, 1.0, v12
	v_mul_f32_e32 v12, 0x3d372713, v3
	v_mul_f32_e32 v15, 0x3d372713, v4
	v_mul_f32_e32 v12, v3, v12
	v_mul_f32_e32 v13, v8, v13
	v_mul_f32_e32 v15, v4, v15
	v_fma_f32 v12, v3, v12, v3
	v_fma_f32 v13, v8, v13, v8
	v_fma_f32 v15, v4, v15, v4
	v_mul_f32_e32 v12, 0x3fcc422a, v12
	v_mul_f32_e32 v13, 0x3fcc422a, v13
	v_mul_f32_e32 v15, 0x3fcc422a, v15
	v_mul_f32_e32 v12, 0xbfb8aa3b, v12
	v_mul_f32_e32 v13, 0xbfb8aa3b, v13
	v_mul_f32_e32 v15, 0xbfb8aa3b, v15
	v_exp_f32_e32 v12, v12
	v_exp_f32_e32 v13, v13
	v_exp_f32_e32 v15, v15
	v_mul_f32_e32 v10, 0x3d372713, v6
	v_add_f32_e32 v18, 1.0, v12
	v_add_f32_e32 v12, 1.0, v13
	v_add_f32_e32 v13, 1.0, v15
	v_mul_f32_e32 v15, 0x3d372713, v9
	v_mul_f32_e32 v16, 0x3d372713, v5
	v_mul_f32_e32 v10, v6, v10
	v_mul_f32_e32 v15, v9, v15
	v_mul_f32_e32 v16, v5, v16
	v_fma_f32 v10, v6, v10, v6
	v_fma_f32 v15, v9, v15, v9
	v_fma_f32 v16, v5, v16, v5
	v_mul_f32_e32 v10, 0x3fcc422a, v10
	v_mul_f32_e32 v15, 0x3fcc422a, v15
	v_mul_f32_e32 v16, 0x3fcc422a, v16
	v_mul_f32_e32 v10, 0xbfb8aa3b, v10
	v_mul_f32_e32 v15, 0xbfb8aa3b, v15
	v_mul_f32_e32 v16, 0xbfb8aa3b, v16
	v_exp_f32_e32 v10, v10
	v_exp_f32_e32 v15, v15
	v_exp_f32_e32 v17, v16
	v_rcp_f32_e32 v16, v13
	v_add_f32_e32 v10, 1.0, v10
	v_add_f32_e32 v13, 1.0, v15
	v_add_f32_e32 v15, 1.0, v17
	v_rcp_f32_e32 v10, v10
	v_rcp_f32_e32 v11, v11
	v_rcp_f32_e32 v12, v12
	v_rcp_f32_e32 v13, v13
	v_rcp_f32_e32 v17, v15
	v_rcp_f32_e32 v15, v18
	v_pk_mul_f32 v[10:11], v[6:7], v[10:11]
	v_pk_mul_f32 v[12:13], v[8:9], v[12:13]
	v_pk_mul_f32 v[16:17], v[4:5], v[16:17]
	v_pk_mul_f32 v[14:15], v[2:3], v[14:15]

.LBB0_469:
	v_cvt_pk_bf16_f32 v50, v10, v11
	v_cvt_pk_bf16_f32 v51, v12, v13
	v_cvt_pk_bf16_f32 v52, v14, v15
	v_cvt_pk_bf16_f32 v53, v16, v17
	s_and_b64 vcc, exec, s[38:39]
	s_mov_b64 s[14:15], -1
	global_store_dwordx4 v[66:67], v[50:53], off offset:256 nt
	s_cbranch_vccnz .LBB0_262

.LBB0_703:
	v_sub_u32_e64 v0, s0, 4 clamp
	v_ashrrev_i32_e32 v57, 3, v152
	v_readfirstlane_b32 s0, v0
	v_sub_u32_e64 v0, v61, 8 clamp
	v_lshrrev_b32_e32 v5, 2, v57
	v_min_u32_e32 v2, 48, v0
	v_and_b32_e32 v3, 7, v152
	v_bfe_u32 v0, v57, 1, 1
	v_and_b32_e32 v5, 6, v5
	v_bitop3_b32 v0, v0, v3, v5 bitop3:0x36
	v_lshl_add_u32 v65, v0, 4, 0
	v_lshlrev_b32_e32 v0, 3, v152
	v_and_b32_e32 v64, 56, v0
	v_lshlrev_b32_e32 v0, 4, v152
	v_and_b32_e32 v0, 0x3f0, v0
	v_lshrrev_b32_e32 v5, 5, v152
	s_and_b64 s[38:39], s[40:41], exec
	v_lshl_add_u64 v[66:67], s[16:17], 0, v[0:1]
	v_bfe_u32 v0, v152, 4, 1
	v_and_b32_e32 v5, 6, v5
	s_cselect_b32 s1, 24, 0xf8
	v_bitop3_b32 v0, v0, v3, v5 bitop3:0x36
	s_min_u32 s66, s0, s1
	v_readlane_b32 s0, v255, 21
	v_lshl_add_u32 v83, v0, 4, 0
	v_lshlrev_b32_e32 v0, 1, v199
	v_add_u32_e32 v88, s82, v150
	v_lshl_add_u32 v4, v193, 2, s0
	s_add_i32 s10, 0, 0x12000
	s_add_i32 s20, s59, -1
	s_and_b32 s83, s25, 4
	v_and_b32_e32 v85, 24, v0
	s_and_b32 s0, s25, -4
	v_add_u32_e32 v0, 16, v2
	v_or_b32_e32 v120, 4, v88
	s_cmp_eq_u32 s0, 4
	v_cmp_ge_i32_e32 vcc, v120, v2
	v_cmp_lt_i32_e64 s[40:41], v120, v0
	s_cselect_b64 s[80:81], -1, 0
	s_and_b64 s[40:41], vcc, s[40:41]
	v_cmp_ge_i32_e32 vcc, v88, v2
	v_cmp_lt_i32_e64 s[42:43], v88, v0
	v_or_b32_e32 v121, 1, v88
	s_and_b64 s[42:43], vcc, s[42:43]
	v_cmp_ge_i32_e32 vcc, v121, v2
	v_cmp_lt_i32_e64 s[44:45], v121, v0
	v_or_b32_e32 v122, 2, v88
	s_and_b64 s[44:45], vcc, s[44:45]
	v_cmp_ge_i32_e32 vcc, v122, v2
	v_cmp_lt_i32_e64 s[46:47], v122, v0
	v_or_b32_e32 v123, 3, v88
	s_and_b64 s[46:47], vcc, s[46:47]
	v_cmp_ge_i32_e32 vcc, v123, v2
	v_cmp_lt_i32_e64 s[48:49], v123, v0
	v_or_b32_e32 v124, 5, v88
	s_and_b64 s[48:49], vcc, s[48:49]
	v_cmp_ge_i32_e32 vcc, v124, v2
	v_cmp_lt_i32_e64 s[50:51], v124, v0
	v_or_b32_e32 v125, 6, v88
	v_or_b32_e32 v126, 7, v88
	v_lshl_add_u32 v60, v3, 4, s10
	v_and_b32_e32 v3, -16, v193
	s_and_b64 s[50:51], vcc, s[50:51]
	v_cmp_ge_i32_e32 vcc, v125, v2
	v_cmp_lt_i32_e64 s[52:53], v125, v0
	v_cmp_lt_i32_e64 s[54:55], v126, v0
	v_mul_u32_u24_e32 v0, 0x410, v199
	s_movk_i32 s35, 0x410
	s_mul_i32 s26, s58, 0xa00
	v_add_u32_e32 v5, 0x200, v152
	v_add_u32_e32 v6, 0x400, v152
	v_add_u32_e32 v7, 0x600, v152
	v_add_u32_e32 v8, 0x800, v152
	v_add_u32_e32 v9, 0xa00, v152
	v_add_u32_e32 v10, 0xc00, v152
	v_add_u32_e32 v11, 0xe00, v152
	s_and_b64 s[52:53], vcc, s[52:53]
	v_cmp_ge_i32_e32 vcc, v126, v2
	v_add3_u32 v127, s10, v3, v0
	v_mov_b32_e32 v2, v1
	v_mov_b32_e32 v3, v1
	v_mad_u64_u32 v[62:63], s[38:39], v57, s35, v[60:61]
	v_ashrrev_i32_e32 v89, 6, v152
	v_ashrrev_i32_e32 v90, 3, v5
	v_ashrrev_i32_e32 v91, 6, v5
	v_ashrrev_i32_e32 v92, 3, v6
	v_ashrrev_i32_e32 v93, 6, v6
	v_ashrrev_i32_e32 v94, 3, v7
	v_ashrrev_i32_e32 v95, 6, v7
	v_ashrrev_i32_e32 v96, 3, v8
	v_ashrrev_i32_e32 v97, 6, v8
	v_ashrrev_i32_e32 v98, 3, v9
	v_ashrrev_i32_e32 v99, 6, v9
	v_ashrrev_i32_e32 v100, 3, v10
	v_ashrrev_i32_e32 v101, 6, v10
	v_ashrrev_i32_e32 v102, 3, v11
	v_ashrrev_i32_e32 v103, 6, v11
	v_lshrrev_b32_e32 v106, 9, v5
	v_lshrrev_b32_e32 v108, 9, v6
	v_lshrrev_b32_e32 v110, 9, v7
	v_lshrrev_b32_e32 v112, 9, v8
	v_lshrrev_b32_e32 v114, 9, v9
	v_lshrrev_b32_e32 v116, 9, v10
	v_lshrrev_b32_e32 v118, 9, v11
	v_mov_b32_e32 v0, v1
	v_add_u32_e32 v128, s26, v4
	v_mov_b64_e32 v[6:7], v[2:3]
	v_mov_b64_e32 v[10:11], v[2:3]
	s_mov_b32 s1, 2
	v_lshrrev_b32_e32 v63, 3, v152
	v_bfe_u32 v82, v152, 3, 6
	s_mov_b32 s38, -1
	v_add_u32_e32 v84, 0x200, v57
	v_and_b32_e32 v86, 3, v193
	v_add_u32_e32 v87, 4, v198
	v_lshrrev_b32_e32 v104, 9, v152
	v_mul_lo_u32 v105, v89, s35
	v_mul_lo_u32 v107, v91, s35
	v_mul_lo_u32 v109, v93, s35
	v_mul_lo_u32 v111, v95, s35
	v_mul_lo_u32 v113, v97, s35
	v_mul_lo_u32 v115, v99, s35
	v_mul_lo_u32 v117, v101, s35
	v_mul_lo_u32 v119, v103, s35
	s_and_b64 s[54:55], vcc, s[54:55]
	v_mov_b32_e32 v129, 0
	v_mov_b32_e32 v130, 0
	v_mov_b32_e32 v131, 0
	v_mov_b32_e32 v132, 0
	v_mov_b32_e32 v133, 0
	v_mov_b32_e32 v134, 0
	v_mov_b32_e32 v135, 0
	v_mov_b32_e32 v136, 0
	v_mov_b32_e32 v137, 0
	v_mov_b32_e32 v138, 0
	v_mov_b32_e32 v139, 0
	v_mov_b32_e32 v140, 0
	v_mov_b32_e32 v141, 0
	v_mov_b32_e32 v142, 0
	v_mov_b32_e32 v143, 0
	v_mov_b32_e32 v144, 0
	v_mov_b32_e32 v145, 0
	v_mov_b32_e32 v146, 0
	v_mov_b32_e32 v147, 0
	v_mov_b32_e32 v148, 0
	v_mov_b32_e32 v149, 0
	v_mov_b32_e32 v152, 0
	v_mov_b32_e32 v154, 0
	v_mov_b32_e32 v155, 0
	v_mov_b32_e32 v156, 0
	v_mov_b32_e32 v157, 0
	v_mov_b32_e32 v158, 0
	v_mov_b32_e32 v159, 0
	v_mov_b32_e32 v160, 0
	v_mov_b32_e32 v161, 0
	v_mov_b32_e32 v162, 0
	v_mov_b32_e32 v163, 0
	v_mov_b64_e32 v[4:5], v[0:1]
	v_mov_b64_e32 v[8:9], v[0:1]
	s_waitcnt vmcnt(0)
	s_branch .LBB0_705

.LBB0_705:
	s_mul_hi_i32 s26, s21, 0x2aaaaaab
	s_ashr_i32 s56, s26, 1
	s_lshr_b32 s57, s26, 31
	s_ashr_i32 s26, s26, 3
	s_add_i32 s56, s56, s57
	s_add_i32 s26, s26, s57
	s_and_b32 s90, s56, 3
	s_mul_i32 s26, s26, 12
	s_mul_i32 s56, s56, 12
	s_sub_i32 s26, s26, s56
	s_add_i32 s26, s21, s26
	s_lshl_b32 s56, s26, 6
	s_cmpk_lt_i32 s26, 0x100
	s_cselect_b32 s57, 31, 0xff
	s_mov_b32 s35, s62
	s_mov_b32 s39, s63
	s_cselect_b32 s62, s11, 0xffffc000
	s_cselect_b32 s63, 24, 0xf8
	s_and_b32 s70, s57, s26
	v_sub_u32_e64 v0, s70, 4 clamp
	s_bitcmp1_b32 s25, 2
	s_cbranch_scc1 .Lna_half1
	s_waitcnt vmcnt(4)
	s_branch .Lna_wdone

.Lna_wdone:
	v_mov_b64_e32 v[22:23], v[18:19]
	v_readfirstlane_b32 s26, v0
	v_mov_b64_e32 v[26:27], v[14:15]
	s_and_b32 s71, s62, s56
	s_min_u32 s91, s26, s63
	s_mov_b32 s10, s66
	v_mov_b64_e32 v[20:21], v[16:17]
	v_mov_b64_e32 v[24:25], v[12:13]
	v_mov_b64_e32 v[2:3], v[74:75]
	v_mov_b64_e32 v[76:77], v[72:73]
	v_mov_b64_e32 v[78:79], v[70:71]
	v_mov_b64_e32 v[80:81], v[68:69]
	s_mov_b64 s[56:57], -1
	s_cmp_gt_i32 s1, 1
	v_lshlrev_b32_e32 v0, 1, v64
	s_cbranch_scc0 .LBB0_707
	s_lshl_b32 s26, s91, 6
	s_add_i32 s56, s26, s71
	s_lshl_b32 s26, s90, 6
	v_add_u32_e32 v12, s56, v57
	v_mov_b64_e32 v[176:177], s[14:15]
	s_or_b32 s66, s26, 0x200
	s_ashr_i32 s57, s56, 31
	v_mad_i64_i32 v[12:13], s[62:63], v12, s9, v[176:177]
	s_lshl_b32 s26, s90, 7
	v_lshl_add_u64 v[180:181], s[56:57], 1, v[66:67]
	v_lshl_add_u64 v[12:13], v[12:13], 0, s[26:27]
	v_add_u32_e32 v14, s66, v89
	v_lshl_add_u64 v[12:13], v[12:13], 0, v[0:1]
	v_mad_i64_i32 v[16:17], s[62:63], v14, s8, v[180:181]
	global_load_dwordx4 v[12:15], v[12:13], off offset:3584
	s_nop 0
	global_load_dwordx4 v[16:19], v[16:17], off
	v_add_u32_e32 v28, s56, v90
	v_mad_i64_i32 v[28:29], s[62:63], v28, s9, v[176:177]
	v_lshl_add_u64 v[28:29], v[28:29], 0, s[26:27]
	v_add_u32_e32 v30, s66, v91
	v_lshl_add_u64 v[28:29], v[28:29], 0, v[0:1]
	v_mad_i64_i32 v[32:33], s[62:63], v30, s8, v[180:181]
	global_load_dwordx4 v[28:31], v[28:29], off offset:3584
	s_nop 0
	global_load_dwordx4 v[32:35], v[32:33], off
	v_add_u32_e32 v36, s56, v92
	v_mad_i64_i32 v[36:37], s[62:63], v36, s9, v[176:177]
	v_lshl_add_u64 v[36:37], v[36:37], 0, s[26:27]
	v_add_u32_e32 v38, s66, v93
	v_lshl_add_u64 v[36:37], v[36:37], 0, v[0:1]
	v_mad_i64_i32 v[40:41], s[62:63], v38, s8, v[180:181]
	global_load_dwordx4 v[36:39], v[36:37], off offset:3584
	s_nop 0
	global_load_dwordx4 v[40:43], v[40:41], off
	v_add_u32_e32 v44, s56, v94
	v_mad_i64_i32 v[44:45], s[62:63], v44, s9, v[176:177]
	v_lshl_add_u64 v[44:45], v[44:45], 0, s[26:27]
	v_add_u32_e32 v46, s66, v95
	v_lshl_add_u64 v[44:45], v[44:45], 0, v[0:1]
	v_mad_i64_i32 v[48:49], s[62:63], v46, s8, v[180:181]
	global_load_dwordx4 v[44:47], v[44:45], off offset:3584
	s_nop 0
	global_load_dwordx4 v[48:51], v[48:49], off
	v_add_u32_e32 v52, s56, v96
	v_mad_i64_i32 v[52:53], s[62:63], v52, s9, v[176:177]
	v_lshl_add_u64 v[52:53], v[52:53], 0, s[26:27]
	v_add_u32_e32 v54, s66, v97
	v_lshl_add_u64 v[52:53], v[52:53], 0, v[0:1]
	v_mad_i64_i32 v[68:69], s[62:63], v54, s8, v[180:181]
	global_load_dwordx4 v[52:55], v[52:53], off offset:3584
	s_nop 0
	global_load_dwordx4 v[68:71], v[68:69], off
	v_add_u32_e32 v72, s56, v98
	v_mad_i64_i32 v[72:73], s[62:63], v72, s9, v[176:177]
	v_lshl_add_u64 v[72:73], v[72:73], 0, s[26:27]
	v_add_u32_e32 v74, s66, v99
	v_lshl_add_u64 v[72:73], v[72:73], 0, v[0:1]
	v_mad_i64_i32 v[164:165], s[62:63], v74, s8, v[180:181]
	global_load_dwordx4 v[72:75], v[72:73], off offset:3584
	s_nop 0
	global_load_dwordx4 v[164:167], v[164:165], off
	v_add_u32_e32 v168, s56, v100
	v_mad_i64_i32 v[168:169], s[62:63], v168, s9, v[176:177]
	v_lshl_add_u64 v[168:169], v[168:169], 0, s[26:27]
	v_add_u32_e32 v170, s66, v101
	v_lshl_add_u64 v[168:169], v[168:169], 0, v[0:1]
	v_mad_i64_i32 v[172:173], s[62:63], v170, s8, v[180:181]
	v_add_u32_e32 v178, s56, v102
	global_load_dwordx4 v[168:171], v[168:169], off offset:3584
	s_nop 0
	global_load_dwordx4 v[172:175], v[172:173], off
	v_mad_i64_i32 v[176:177], s[56:57], v178, s9, v[176:177]
	v_lshl_add_u64 v[176:177], v[176:177], 0, s[26:27]
	v_lshl_add_u64 v[176:177], v[176:177], 0, v[0:1]
	v_add_u32_e32 v182, s66, v103
	global_load_dwordx4 v[176:179], v[176:177], off offset:3584
	v_mad_i64_i32 v[180:181], s[56:57], v182, s8, v[180:181]
	global_load_dwordx4 v[180:183], v[180:181], off
	v_add_lshl_u32 v184, s91, v63, 7
	v_add_lshl_u32 v185, s91, v104, 6
	v_and_b32_e32 v184, 0x380, v184
	v_and_or_b32 v185, v185, s34, v82
	v_add_u32_e32 v184, v60, v184
	v_lshl_add_u32 v185, v185, 7, v83
	s_mov_b64 s[56:57], 0
	s_waitcnt vmcnt(15)
	ds_write_b128 v185, v[12:15]
	v_add_u32_e32 v12, v184, v105
	s_waitcnt vmcnt(14)
	ds_write_b128 v12, v[16:19]
	v_add_lshl_u32 v12, s91, v106, 6
	v_and_or_b32 v12, v12, s34, v82
	v_lshl_add_u32 v12, v12, 7, v83
	s_waitcnt vmcnt(13)
	ds_write_b128 v12, v[28:31]
	v_add_u32_e32 v12, v184, v107
	s_waitcnt vmcnt(12)
	ds_write_b128 v12, v[32:35]
	v_add_lshl_u32 v12, s91, v108, 6
	v_and_or_b32 v12, v12, s34, v82
	v_lshl_add_u32 v12, v12, 7, v83
	s_waitcnt vmcnt(11)
	ds_write_b128 v12, v[36:39]
	v_add_u32_e32 v12, v184, v109
	s_waitcnt vmcnt(10)
	ds_write_b128 v12, v[40:43]
	v_add_lshl_u32 v12, s91, v110, 6
	v_and_or_b32 v12, v12, s34, v82
	v_lshl_add_u32 v12, v12, 7, v83
	s_waitcnt vmcnt(9)
	ds_write_b128 v12, v[44:47]
	v_add_u32_e32 v12, v184, v111
	s_waitcnt vmcnt(8)
	ds_write_b128 v12, v[48:51]
	v_add_lshl_u32 v12, s91, v112, 6
	v_and_or_b32 v12, v12, s34, v82
	v_lshl_add_u32 v12, v12, 7, v83
	s_waitcnt vmcnt(7)
	ds_write_b128 v12, v[52:55]
	v_add_u32_e32 v12, v184, v113
	s_waitcnt vmcnt(6)
	ds_write_b128 v12, v[68:71]
	v_add_lshl_u32 v12, s91, v114, 6
	v_and_or_b32 v12, v12, s34, v82
	v_lshl_add_u32 v12, v12, 7, v83
	s_waitcnt vmcnt(5)
	ds_write_b128 v12, v[72:75]
	v_add_u32_e32 v12, v184, v115
	s_waitcnt vmcnt(4)
	ds_write_b128 v12, v[164:167]
	v_add_lshl_u32 v12, s91, v116, 6
	v_and_or_b32 v12, v12, s34, v82
	v_lshl_add_u32 v12, v12, 7, v83
	s_waitcnt vmcnt(3)
	ds_write_b128 v12, v[168:171]
	v_add_u32_e32 v12, v184, v117
	s_waitcnt vmcnt(2)
	ds_write_b128 v12, v[172:175]
	v_add_lshl_u32 v12, s91, v118, 6
	v_and_or_b32 v12, v12, s34, v82
	v_lshl_add_u32 v12, v12, 7, v83
	s_waitcnt vmcnt(1)
	ds_write_b128 v12, v[176:179]
	v_add_u32_e32 v12, v184, v119
	s_waitcnt vmcnt(0)
	ds_write_b128 v12, v[180:183]
